# GEMM loops: loader segments at s_setprio 1, MFMA clusters at 0 (inverse of the template)
# speedup vs baseline: 1.0002x; 1.0002x over previous
.LBB0_238:
	v_add_u32_e32 v142, s85, v180
	v_add_u32_e32 v158, s86, v180
	ds_read_b128 v[130:133], v142
	ds_read_b128 v[134:137], v142 offset:1024
	ds_read_b128 v[138:141], v142 offset:2048
	ds_read_b128 v[142:145], v142 offset:3072
	ds_read_b128 v[146:149], v158
	ds_read_b128 v[172:175], v158 offset:1024
	ds_read_b128 v[176:179], v158 offset:2048
	ds_read_b128 v[210:213], v158 offset:3072
	s_add_u32 s60, s6, 0xfffc0080
	s_addc_u32 s61, s7, -1
	s_cmp_eq_u32 s96, 12
	s_cselect_b32 s69, s9, s61
	s_cselect_b32 s68, s45, s60
	s_cselect_b32 s67, s43, s95
	s_cselect_b32 s66, s93, s94
	v_lshl_add_u64 v[246:247], s[6:7], 0, v[164:165]
	s_add_i32 m0, s41, 0xc000
	ds_read_b128 v[214:217], v204
	ds_read_b128 v[218:221], v204 offset:1024
	ds_read_b128 v[222:225], v204 offset:2048
	ds_read_b128 v[226:229], v204 offset:3072
	ds_read_b128 v[230:233], v204 offset:4096
	ds_read_b128 v[234:237], v204 offset:5120
	ds_read_b128 v[238:241], v204 offset:6144
	ds_read_b128 v[242:245], v204 offset:7168
	global_load_lds_dwordx4 v[246:247], off
	v_lshl_add_u64 v[246:247], s[6:7], 0, v[166:167]
	s_add_i32 m0, s41, 0xe000
	s_nop 0
	global_load_lds_dwordx4 v[246:247], off
	s_waitcnt vmcnt(8)
	s_waitcnt lgkmcnt(0)
	s_barrier
	s_setprio 0
	s_waitcnt lgkmcnt(0)
	v_mfma_f32_16x16x32_bf16 v[126:129], v[130:133], v[214:217], v[126:129]
	v_mfma_f32_16x16x32_bf16 v[122:125], v[138:141], v[214:217], v[122:125]
	v_mfma_f32_16x16x32_bf16 v[118:121], v[130:133], v[222:225], v[118:121]
	v_mfma_f32_16x16x32_bf16 v[110:113], v[138:141], v[222:225], v[110:113]
	v_mfma_f32_16x16x32_bf16 v[102:105], v[130:133], v[230:233], v[102:105]
	v_mfma_f32_16x16x32_bf16 v[94:97], v[138:141], v[230:233], v[94:97]
	v_mfma_f32_16x16x32_bf16 v[86:89], v[130:133], v[238:241], v[86:89]
	v_mfma_f32_16x16x32_bf16 v[78:81], v[138:141], v[238:241], v[78:81]
	v_mfma_f32_16x16x32_bf16 v[126:129], v[134:137], v[218:221], v[126:129]
	v_mfma_f32_16x16x32_bf16 v[122:125], v[142:145], v[218:221], v[122:125]
	v_mfma_f32_16x16x32_bf16 v[118:121], v[134:137], v[226:229], v[118:121]
	v_mfma_f32_16x16x32_bf16 v[110:113], v[142:145], v[226:229], v[110:113]
	v_mfma_f32_16x16x32_bf16 v[102:105], v[134:137], v[234:237], v[102:105]
	v_mfma_f32_16x16x32_bf16 v[94:97], v[142:145], v[234:237], v[94:97]
	v_mfma_f32_16x16x32_bf16 v[86:89], v[134:137], v[242:245], v[86:89]
	v_mfma_f32_16x16x32_bf16 v[78:81], v[142:145], v[242:245], v[78:81]
	v_mfma_f32_16x16x32_bf16 v[114:117], v[146:149], v[214:217], v[114:117]
	v_mfma_f32_16x16x32_bf16 v[106:109], v[176:179], v[214:217], v[106:109]
	v_mfma_f32_16x16x32_bf16 v[98:101], v[146:149], v[222:225], v[98:101]
	v_mfma_f32_16x16x32_bf16 v[90:93], v[176:179], v[222:225], v[90:93]
	v_mfma_f32_16x16x32_bf16 v[82:85], v[146:149], v[230:233], v[82:85]
	v_mfma_f32_16x16x32_bf16 v[74:77], v[176:179], v[230:233], v[74:77]
	v_mfma_f32_16x16x32_bf16 v[70:73], v[146:149], v[238:241], v[70:73]
	v_mfma_f32_16x16x32_bf16 v[66:69], v[176:179], v[238:241], v[66:69]
	v_mfma_f32_16x16x32_bf16 v[114:117], v[172:175], v[218:221], v[114:117]
	v_mfma_f32_16x16x32_bf16 v[106:109], v[210:213], v[218:221], v[106:109]
	v_mfma_f32_16x16x32_bf16 v[98:101], v[172:175], v[226:229], v[98:101]
	v_mfma_f32_16x16x32_bf16 v[90:93], v[210:213], v[226:229], v[90:93]
	v_mfma_f32_16x16x32_bf16 v[82:85], v[172:175], v[234:237], v[82:85]
	v_mfma_f32_16x16x32_bf16 v[74:77], v[210:213], v[234:237], v[74:77]
	v_mfma_f32_16x16x32_bf16 v[70:73], v[172:175], v[242:245], v[70:73]
	v_mfma_f32_16x16x32_bf16 v[66:69], v[210:213], v[242:245], v[66:69]
	s_setprio 1
	s_barrier
	s_add_i32 s60, s85, s3
	v_lshl_add_u64 v[246:247], s[66:67], 0, v[152:153]
	s_mov_b32 m0, s60
	ds_read_b128 v[214:217], v204 offset:16384
	ds_read_b128 v[218:221], v204 offset:17408
	ds_read_b128 v[222:225], v204 offset:18432
	ds_read_b128 v[226:229], v204 offset:19456
	ds_read_b128 v[230:233], v204 offset:20480
	ds_read_b128 v[234:237], v204 offset:21504
	ds_read_b128 v[238:241], v204 offset:22528
	ds_read_b128 v[242:245], v204 offset:23552
	global_load_lds_dwordx4 v[246:247], off
	s_add_i32 m0, s60, 0x2000
	s_add_u32 s60, s66, 0x40000
	v_lshl_add_u64 v[248:249], s[66:67], 0, v[156:157]
	s_addc_u32 s61, s67, 0
	s_add_i32 s97, s86, s3
	global_load_lds_dwordx4 v[248:249], off
	v_lshl_add_u64 v[250:251], s[60:61], 0, v[152:153]
	s_mov_b32 m0, s97
	v_lshl_add_u64 v[252:253], s[68:69], 0, v[154:155]
	global_load_lds_dwordx4 v[250:251], off
	v_lshl_add_u64 v[250:251], s[60:61], 0, v[156:157]
	s_add_i32 m0, s97, 0x2000
	s_nop 0
	global_load_lds_dwordx4 v[250:251], off
	v_lshl_add_u64 v[250:251], s[68:69], 0, v[150:151]
	s_mov_b32 m0, s41
	s_nop 0
	global_load_lds_dwordx4 v[250:251], off
	s_mov_b32 m0, s70
	s_nop 0
	global_load_lds_dwordx4 v[252:253], off
	s_waitcnt vmcnt(8)
	s_waitcnt lgkmcnt(0)
	s_barrier
	s_setprio 0
	s_waitcnt lgkmcnt(0)
	v_mfma_f32_16x16x32_bf16 v[62:65], v[130:133], v[214:217], v[62:65]
	v_mfma_f32_16x16x32_bf16 v[58:61], v[138:141], v[214:217], v[58:61]
	v_mfma_f32_16x16x32_bf16 v[54:57], v[130:133], v[222:225], v[54:57]
	v_mfma_f32_16x16x32_bf16 v[46:49], v[138:141], v[222:225], v[46:49]
	v_mfma_f32_16x16x32_bf16 v[38:41], v[130:133], v[230:233], v[38:41]
	v_mfma_f32_16x16x32_bf16 v[30:33], v[138:141], v[230:233], v[30:33]
	v_mfma_f32_16x16x32_bf16 v[22:25], v[130:133], v[238:241], v[22:25]
	v_mfma_f32_16x16x32_bf16 v[14:17], v[138:141], v[238:241], v[14:17]
	v_mfma_f32_16x16x32_bf16 v[62:65], v[134:137], v[218:221], v[62:65]
	v_mfma_f32_16x16x32_bf16 v[58:61], v[142:145], v[218:221], v[58:61]
	v_mfma_f32_16x16x32_bf16 v[54:57], v[134:137], v[226:229], v[54:57]
	v_mfma_f32_16x16x32_bf16 v[46:49], v[142:145], v[226:229], v[46:49]
	v_mfma_f32_16x16x32_bf16 v[38:41], v[134:137], v[234:237], v[38:41]
	v_mfma_f32_16x16x32_bf16 v[30:33], v[142:145], v[234:237], v[30:33]
	v_mfma_f32_16x16x32_bf16 v[22:25], v[134:137], v[242:245], v[22:25]
	v_mfma_f32_16x16x32_bf16 v[14:17], v[142:145], v[242:245], v[14:17]
	v_mfma_f32_16x16x32_bf16 v[50:53], v[146:149], v[214:217], v[50:53]
	v_mfma_f32_16x16x32_bf16 v[42:45], v[176:179], v[214:217], v[42:45]
	v_mfma_f32_16x16x32_bf16 v[34:37], v[146:149], v[222:225], v[34:37]
	v_mfma_f32_16x16x32_bf16 v[26:29], v[176:179], v[222:225], v[26:29]
	v_mfma_f32_16x16x32_bf16 v[18:21], v[146:149], v[230:233], v[18:21]
	v_mfma_f32_16x16x32_bf16 v[10:13], v[176:179], v[230:233], v[10:13]
	v_mfma_f32_16x16x32_bf16 v[6:9], v[146:149], v[238:241], v[6:9]
	v_mfma_f32_16x16x32_bf16 v[2:5], v[176:179], v[238:241], v[2:5]
	v_mfma_f32_16x16x32_bf16 v[50:53], v[172:175], v[218:221], v[50:53]
	v_mfma_f32_16x16x32_bf16 v[42:45], v[210:213], v[218:221], v[42:45]
	v_mfma_f32_16x16x32_bf16 v[34:37], v[172:175], v[226:229], v[34:37]
	v_mfma_f32_16x16x32_bf16 v[26:29], v[210:213], v[226:229], v[26:29]
	v_mfma_f32_16x16x32_bf16 v[18:21], v[172:175], v[234:237], v[18:21]
	v_mfma_f32_16x16x32_bf16 v[10:13], v[210:213], v[234:237], v[10:13]
	v_mfma_f32_16x16x32_bf16 v[6:9], v[172:175], v[242:245], v[6:9]
	v_mfma_f32_16x16x32_bf16 v[2:5], v[210:213], v[242:245], v[2:5]
	s_setprio 1
	s_barrier
	s_add_i32 s97, 0, 0x18000
	s_add_i32 vcc_lo, 0, 0x1c000
	v_add_u32_e32 v142, s97, v180
	v_add_u32_e32 v158, vcc_lo, v180
	ds_read_b128 v[130:133], v142
	ds_read_b128 v[134:137], v142 offset:1024
	ds_read_b128 v[138:141], v142 offset:2048
	ds_read_b128 v[142:145], v142 offset:3072
	ds_read_b128 v[146:149], v158
	ds_read_b128 v[172:175], v158 offset:1024
	ds_read_b128 v[176:179], v158 offset:2048
	ds_read_b128 v[210:213], v158 offset:3072
	s_add_u32 s60, s68, 0x40000
	s_addc_u32 s61, s69, 0
	s_mov_b32 m0, s71
	v_lshl_add_u64 v[170:171], s[60:61], 0, v[150:151]
	ds_read_b128 v[214:217], v204 offset:32768
	ds_read_b128 v[218:221], v204 offset:33792
	ds_read_b128 v[222:225], v204 offset:34816
	ds_read_b128 v[226:229], v204 offset:35840
	ds_read_b128 v[230:233], v204 offset:36864
	ds_read_b128 v[234:237], v204 offset:37888
	ds_read_b128 v[238:241], v204 offset:38912
	ds_read_b128 v[242:245], v204 offset:39936
	global_load_lds_dwordx4 v[170:171], off
	v_lshl_add_u64 v[170:171], s[60:61], 0, v[154:155]
	s_mov_b32 m0, s72
	s_nop 0
	global_load_lds_dwordx4 v[170:171], off
	s_waitcnt vmcnt(8)
	s_waitcnt lgkmcnt(0)
	s_barrier
	s_setprio 0
	s_waitcnt lgkmcnt(0)
	v_mfma_f32_16x16x32_bf16 v[126:129], v[130:133], v[214:217], v[126:129]
	v_mfma_f32_16x16x32_bf16 v[122:125], v[138:141], v[214:217], v[122:125]
	v_mfma_f32_16x16x32_bf16 v[118:121], v[130:133], v[222:225], v[118:121]
	v_mfma_f32_16x16x32_bf16 v[110:113], v[138:141], v[222:225], v[110:113]
	v_mfma_f32_16x16x32_bf16 v[102:105], v[130:133], v[230:233], v[102:105]
	v_mfma_f32_16x16x32_bf16 v[94:97], v[138:141], v[230:233], v[94:97]
	v_mfma_f32_16x16x32_bf16 v[86:89], v[130:133], v[238:241], v[86:89]
	v_mfma_f32_16x16x32_bf16 v[78:81], v[138:141], v[238:241], v[78:81]
	v_mfma_f32_16x16x32_bf16 v[126:129], v[134:137], v[218:221], v[126:129]
	v_mfma_f32_16x16x32_bf16 v[122:125], v[142:145], v[218:221], v[122:125]
	v_mfma_f32_16x16x32_bf16 v[118:121], v[134:137], v[226:229], v[118:121]
	v_mfma_f32_16x16x32_bf16 v[110:113], v[142:145], v[226:229], v[110:113]
	v_mfma_f32_16x16x32_bf16 v[102:105], v[134:137], v[234:237], v[102:105]
	v_mfma_f32_16x16x32_bf16 v[94:97], v[142:145], v[234:237], v[94:97]
	v_mfma_f32_16x16x32_bf16 v[86:89], v[134:137], v[242:245], v[86:89]
	v_mfma_f32_16x16x32_bf16 v[78:81], v[142:145], v[242:245], v[78:81]
	v_mfma_f32_16x16x32_bf16 v[114:117], v[146:149], v[214:217], v[114:117]
	v_mfma_f32_16x16x32_bf16 v[106:109], v[176:179], v[214:217], v[106:109]
	v_mfma_f32_16x16x32_bf16 v[98:101], v[146:149], v[222:225], v[98:101]
	v_mfma_f32_16x16x32_bf16 v[90:93], v[176:179], v[222:225], v[90:93]
	v_mfma_f32_16x16x32_bf16 v[82:85], v[146:149], v[230:233], v[82:85]
	v_mfma_f32_16x16x32_bf16 v[74:77], v[176:179], v[230:233], v[74:77]
	v_mfma_f32_16x16x32_bf16 v[70:73], v[146:149], v[238:241], v[70:73]
	v_mfma_f32_16x16x32_bf16 v[66:69], v[176:179], v[238:241], v[66:69]
	v_mfma_f32_16x16x32_bf16 v[114:117], v[172:175], v[218:221], v[114:117]
	v_mfma_f32_16x16x32_bf16 v[106:109], v[210:213], v[218:221], v[106:109]
	v_mfma_f32_16x16x32_bf16 v[98:101], v[172:175], v[226:229], v[98:101]
	v_mfma_f32_16x16x32_bf16 v[90:93], v[210:213], v[226:229], v[90:93]
	v_mfma_f32_16x16x32_bf16 v[82:85], v[172:175], v[234:237], v[82:85]
	v_mfma_f32_16x16x32_bf16 v[74:77], v[210:213], v[234:237], v[74:77]
	v_mfma_f32_16x16x32_bf16 v[70:73], v[172:175], v[242:245], v[70:73]
	v_mfma_f32_16x16x32_bf16 v[66:69], v[210:213], v[242:245], v[66:69]
	s_setprio 1
	s_barrier
	s_add_i32 s60, s97, s3
	v_lshl_add_u64 v[170:171], v[246:247], 0, s[28:29]
	s_mov_b32 m0, s60
	ds_read_b128 v[214:217], v204 offset:49152
	ds_read_b128 v[218:221], v204 offset:50176
	ds_read_b128 v[222:225], v204 offset:51200
	ds_read_b128 v[226:229], v204 offset:52224
	ds_read_b128 v[230:233], v204 offset:53248
	ds_read_b128 v[234:237], v204 offset:54272
	ds_read_b128 v[238:241], v204 offset:55296
	ds_read_b128 v[242:245], v204 offset:56320
	global_load_lds_dwordx4 v[170:171], off
	s_add_i32 m0, s60, 0x2000
	s_add_u32 s60, s66, 0x40080
	v_lshl_add_u64 v[170:171], v[248:249], 0, s[28:29]
	s_addc_u32 s61, s67, 0
	s_add_i32 s66, vcc_lo, s3
	global_load_lds_dwordx4 v[170:171], off
	v_lshl_add_u64 v[170:171], s[60:61], 0, v[152:153]
	s_mov_b32 m0, s66
	s_nop 0
	global_load_lds_dwordx4 v[170:171], off
	v_lshl_add_u64 v[170:171], s[60:61], 0, v[156:157]
	s_add_i32 m0, s66, 0x2000
	s_nop 0
	global_load_lds_dwordx4 v[170:171], off
	v_lshl_add_u64 v[170:171], v[250:251], 0, s[28:29]
	s_mov_b32 m0, s76
	s_nop 0
	global_load_lds_dwordx4 v[170:171], off
	v_lshl_add_u64 v[170:171], v[252:253], 0, s[28:29]
	s_mov_b32 m0, s77
	s_nop 0
	global_load_lds_dwordx4 v[170:171], off
	s_waitcnt vmcnt(8)
	s_waitcnt lgkmcnt(0)
	s_barrier
	s_setprio 0
	s_waitcnt lgkmcnt(0)
	v_mfma_f32_16x16x32_bf16 v[62:65], v[130:133], v[214:217], v[62:65]
	v_mfma_f32_16x16x32_bf16 v[58:61], v[138:141], v[214:217], v[58:61]
	v_mfma_f32_16x16x32_bf16 v[54:57], v[130:133], v[222:225], v[54:57]
	v_mfma_f32_16x16x32_bf16 v[46:49], v[138:141], v[222:225], v[46:49]
	v_mfma_f32_16x16x32_bf16 v[38:41], v[130:133], v[230:233], v[38:41]
	v_mfma_f32_16x16x32_bf16 v[30:33], v[138:141], v[230:233], v[30:33]
	v_mfma_f32_16x16x32_bf16 v[22:25], v[130:133], v[238:241], v[22:25]
	v_mfma_f32_16x16x32_bf16 v[14:17], v[138:141], v[238:241], v[14:17]
	v_mfma_f32_16x16x32_bf16 v[62:65], v[134:137], v[218:221], v[62:65]
	v_mfma_f32_16x16x32_bf16 v[58:61], v[142:145], v[218:221], v[58:61]
	v_mfma_f32_16x16x32_bf16 v[54:57], v[134:137], v[226:229], v[54:57]
	v_mfma_f32_16x16x32_bf16 v[46:49], v[142:145], v[226:229], v[46:49]
	v_mfma_f32_16x16x32_bf16 v[38:41], v[134:137], v[234:237], v[38:41]
	v_mfma_f32_16x16x32_bf16 v[30:33], v[142:145], v[234:237], v[30:33]
	v_mfma_f32_16x16x32_bf16 v[22:25], v[134:137], v[242:245], v[22:25]
	v_mfma_f32_16x16x32_bf16 v[14:17], v[142:145], v[242:245], v[14:17]
	v_mfma_f32_16x16x32_bf16 v[50:53], v[146:149], v[214:217], v[50:53]
	v_mfma_f32_16x16x32_bf16 v[42:45], v[176:179], v[214:217], v[42:45]
	v_mfma_f32_16x16x32_bf16 v[34:37], v[146:149], v[222:225], v[34:37]
	v_mfma_f32_16x16x32_bf16 v[26:29], v[176:179], v[222:225], v[26:29]
	v_mfma_f32_16x16x32_bf16 v[18:21], v[146:149], v[230:233], v[18:21]
	v_mfma_f32_16x16x32_bf16 v[10:13], v[176:179], v[230:233], v[10:13]
	v_mfma_f32_16x16x32_bf16 v[6:9], v[146:149], v[238:241], v[6:9]
	v_mfma_f32_16x16x32_bf16 v[2:5], v[176:179], v[238:241], v[2:5]
	v_mfma_f32_16x16x32_bf16 v[50:53], v[172:175], v[218:221], v[50:53]
	v_mfma_f32_16x16x32_bf16 v[42:45], v[210:213], v[218:221], v[42:45]
	v_mfma_f32_16x16x32_bf16 v[34:37], v[172:175], v[226:229], v[34:37]
	v_mfma_f32_16x16x32_bf16 v[26:29], v[210:213], v[226:229], v[26:29]
	v_mfma_f32_16x16x32_bf16 v[18:21], v[172:175], v[234:237], v[18:21]
	v_mfma_f32_16x16x32_bf16 v[10:13], v[210:213], v[234:237], v[10:13]
	v_mfma_f32_16x16x32_bf16 v[6:9], v[172:175], v[242:245], v[6:9]
	v_mfma_f32_16x16x32_bf16 v[2:5], v[210:213], v[242:245], v[2:5]
	s_setprio 1
	s_barrier
	s_add_i32 s96, s96, 2
	s_add_u32 s6, s6, 0x100
	s_addc_u32 s7, s7, 0
	s_add_u32 s94, s94, 0x100
	s_addc_u32 s95, s95, 0
	s_cmp_gt_u32 s96, 13
	s_cbranch_scc0 .LBB0_238
	s_and_b64 vcc, exec, s[30:31]
	s_cbranch_vccnz .LBB0_243
	s_cmp_lg_u32 s8, 5
	s_mov_b64 s[6:7], -1
	s_cbranch_scc1 .LBB0_244

.LBB0_493:
	ds_read_b128 v[74:77], v170
	ds_read_b128 v[78:81], v170 offset:1024
	ds_read_b128 v[154:157], v170 offset:2048
	ds_read_b128 v[158:161], v170 offset:3072
	ds_read_b128 v[162:165], v171
	ds_read_b128 v[174:177], v171 offset:1024
	ds_read_b128 v[178:181], v171 offset:2048
	ds_read_b128 v[182:185], v171 offset:3072
	s_add_u32 s42, s40, 0xfffc0080
	s_addc_u32 s43, s41, -1
	s_cmp_eq_u32 s83, 12
	s_cselect_b32 s45, s25, s43
	s_cselect_b32 s44, s39, s42
	s_cselect_b32 s43, s19, s82
	s_cselect_b32 s42, s80, s81
	v_lshl_add_u64 v[166:167], s[40:41], 0, v[146:147]
	s_add_i32 m0, s64, 0xc000
	ds_read_b128 v[186:189], v172
	ds_read_b128 v[190:193], v172 offset:1024
	ds_read_b128 v[194:197], v172 offset:2048
	ds_read_b128 v[198:201], v172 offset:3072
	ds_read_b128 v[202:205], v172 offset:4096
	ds_read_b128 v[206:209], v172 offset:5120
	ds_read_b128 v[210:213], v172 offset:6144
	ds_read_b128 v[214:217], v172 offset:7168
	global_load_lds_dwordx4 v[166:167], off
	v_lshl_add_u64 v[166:167], s[40:41], 0, v[148:149]
	s_add_i32 m0, s64, 0xe000
	s_nop 0
	global_load_lds_dwordx4 v[166:167], off
	s_waitcnt vmcnt(8)
	s_waitcnt lgkmcnt(0)
	s_barrier
	s_setprio 0
	s_waitcnt lgkmcnt(0)
	v_mfma_f32_16x16x32_bf16 v[86:89], v[74:77], v[186:189], v[86:89]
	v_mfma_f32_16x16x32_bf16 v[82:85], v[154:157], v[186:189], v[82:85]
	v_mfma_f32_16x16x32_bf16 v[126:129], v[74:77], v[194:197], v[126:129]
	v_mfma_f32_16x16x32_bf16 v[122:125], v[154:157], v[194:197], v[122:125]
	v_mfma_f32_16x16x32_bf16 v[110:113], v[74:77], v[202:205], v[110:113]
	v_mfma_f32_16x16x32_bf16 v[106:109], v[154:157], v[202:205], v[106:109]
	v_mfma_f32_16x16x32_bf16 v[94:97], v[74:77], v[210:213], v[94:97]
	v_mfma_f32_16x16x32_bf16 v[90:93], v[154:157], v[210:213], v[90:93]
	v_mfma_f32_16x16x32_bf16 v[86:89], v[78:81], v[190:193], v[86:89]
	v_mfma_f32_16x16x32_bf16 v[82:85], v[158:161], v[190:193], v[82:85]
	v_mfma_f32_16x16x32_bf16 v[126:129], v[78:81], v[198:201], v[126:129]
	v_mfma_f32_16x16x32_bf16 v[122:125], v[158:161], v[198:201], v[122:125]
	v_mfma_f32_16x16x32_bf16 v[110:113], v[78:81], v[206:209], v[110:113]
	v_mfma_f32_16x16x32_bf16 v[106:109], v[158:161], v[206:209], v[106:109]
	v_mfma_f32_16x16x32_bf16 v[94:97], v[78:81], v[214:217], v[94:97]
	v_mfma_f32_16x16x32_bf16 v[90:93], v[158:161], v[214:217], v[90:93]
	v_mfma_f32_16x16x32_bf16 v[134:137], v[162:165], v[186:189], v[134:137]
	v_mfma_f32_16x16x32_bf16 v[130:133], v[178:181], v[186:189], v[130:133]
	v_mfma_f32_16x16x32_bf16 v[118:121], v[162:165], v[194:197], v[118:121]
	v_mfma_f32_16x16x32_bf16 v[114:117], v[178:181], v[194:197], v[114:117]
	v_mfma_f32_16x16x32_bf16 v[102:105], v[162:165], v[202:205], v[102:105]
	v_mfma_f32_16x16x32_bf16 v[98:101], v[178:181], v[202:205], v[98:101]
	v_mfma_f32_16x16x32_bf16 v[70:73], v[162:165], v[210:213], v[70:73]
	v_mfma_f32_16x16x32_bf16 v[66:69], v[178:181], v[210:213], v[66:69]
	v_mfma_f32_16x16x32_bf16 v[134:137], v[174:177], v[190:193], v[134:137]
	v_mfma_f32_16x16x32_bf16 v[130:133], v[182:185], v[190:193], v[130:133]
	v_mfma_f32_16x16x32_bf16 v[118:121], v[174:177], v[198:201], v[118:121]
	v_mfma_f32_16x16x32_bf16 v[114:117], v[182:185], v[198:201], v[114:117]
	v_mfma_f32_16x16x32_bf16 v[102:105], v[174:177], v[206:209], v[102:105]
	v_mfma_f32_16x16x32_bf16 v[98:101], v[182:185], v[206:209], v[98:101]
	v_mfma_f32_16x16x32_bf16 v[70:73], v[174:177], v[214:217], v[70:73]
	v_mfma_f32_16x16x32_bf16 v[66:69], v[182:185], v[214:217], v[66:69]
	s_setprio 1
	s_barrier
	s_add_i32 s60, s77, s63
	v_lshl_add_u64 v[166:167], s[42:43], 0, v[140:141]
	s_mov_b32 m0, s60
	ds_read_b128 v[186:189], v172 offset:16384
	ds_read_b128 v[190:193], v172 offset:17408
	ds_read_b128 v[194:197], v172 offset:18432
	ds_read_b128 v[198:201], v172 offset:19456
	ds_read_b128 v[202:205], v172 offset:20480
	ds_read_b128 v[206:209], v172 offset:21504
	ds_read_b128 v[210:213], v172 offset:22528
	ds_read_b128 v[214:217], v172 offset:23552
	global_load_lds_dwordx4 v[166:167], off
	s_add_i32 m0, s60, 0x2000
	s_add_u32 s60, s42, 0x40000
	v_lshl_add_u64 v[218:219], s[42:43], 0, v[144:145]
	s_addc_u32 s61, s43, 0
	s_add_i32 s84, s78, s63
	global_load_lds_dwordx4 v[218:219], off
	v_lshl_add_u64 v[220:221], s[60:61], 0, v[140:141]
	s_mov_b32 m0, s84
	v_lshl_add_u64 v[222:223], s[44:45], 0, v[142:143]
	global_load_lds_dwordx4 v[220:221], off
	v_lshl_add_u64 v[220:221], s[60:61], 0, v[144:145]
	s_add_i32 m0, s84, 0x2000
	s_nop 0
	global_load_lds_dwordx4 v[220:221], off
	v_lshl_add_u64 v[220:221], s[44:45], 0, v[138:139]
	s_mov_b32 m0, s64
	s_nop 0
	global_load_lds_dwordx4 v[220:221], off
	s_mov_b32 m0, s65
	s_nop 0
	global_load_lds_dwordx4 v[222:223], off
	s_waitcnt vmcnt(8)
	s_waitcnt lgkmcnt(0)
	s_barrier
	s_setprio 0
	s_waitcnt lgkmcnt(0)
	v_mfma_f32_16x16x32_bf16 v[62:65], v[74:77], v[186:189], v[62:65]
	v_mfma_f32_16x16x32_bf16 v[58:61], v[154:157], v[186:189], v[58:61]
	v_mfma_f32_16x16x32_bf16 v[46:49], v[74:77], v[194:197], v[46:49]
	v_mfma_f32_16x16x32_bf16 v[42:45], v[154:157], v[194:197], v[42:45]
	v_mfma_f32_16x16x32_bf16 v[30:33], v[74:77], v[202:205], v[30:33]
	v_mfma_f32_16x16x32_bf16 v[26:29], v[154:157], v[202:205], v[26:29]
	v_mfma_f32_16x16x32_bf16 v[14:17], v[74:77], v[210:213], v[14:17]
	v_mfma_f32_16x16x32_bf16 v[10:13], v[154:157], v[210:213], v[10:13]
	v_mfma_f32_16x16x32_bf16 v[62:65], v[78:81], v[190:193], v[62:65]
	v_mfma_f32_16x16x32_bf16 v[58:61], v[158:161], v[190:193], v[58:61]
	v_mfma_f32_16x16x32_bf16 v[46:49], v[78:81], v[198:201], v[46:49]
	v_mfma_f32_16x16x32_bf16 v[42:45], v[158:161], v[198:201], v[42:45]
	v_mfma_f32_16x16x32_bf16 v[30:33], v[78:81], v[206:209], v[30:33]
	v_mfma_f32_16x16x32_bf16 v[26:29], v[158:161], v[206:209], v[26:29]
	v_mfma_f32_16x16x32_bf16 v[14:17], v[78:81], v[214:217], v[14:17]
	v_mfma_f32_16x16x32_bf16 v[10:13], v[158:161], v[214:217], v[10:13]
	v_mfma_f32_16x16x32_bf16 v[54:57], v[162:165], v[186:189], v[54:57]
	v_mfma_f32_16x16x32_bf16 v[50:53], v[178:181], v[186:189], v[50:53]
	v_mfma_f32_16x16x32_bf16 v[38:41], v[162:165], v[194:197], v[38:41]
	v_mfma_f32_16x16x32_bf16 v[34:37], v[178:181], v[194:197], v[34:37]
	v_mfma_f32_16x16x32_bf16 v[22:25], v[162:165], v[202:205], v[22:25]
	v_mfma_f32_16x16x32_bf16 v[18:21], v[178:181], v[202:205], v[18:21]
	v_mfma_f32_16x16x32_bf16 v[6:9], v[162:165], v[210:213], v[6:9]
	v_mfma_f32_16x16x32_bf16 v[2:5], v[178:181], v[210:213], v[2:5]
	v_mfma_f32_16x16x32_bf16 v[54:57], v[174:177], v[190:193], v[54:57]
	v_mfma_f32_16x16x32_bf16 v[50:53], v[182:185], v[190:193], v[50:53]
	v_mfma_f32_16x16x32_bf16 v[38:41], v[174:177], v[198:201], v[38:41]
	v_mfma_f32_16x16x32_bf16 v[34:37], v[182:185], v[198:201], v[34:37]
	v_mfma_f32_16x16x32_bf16 v[22:25], v[174:177], v[206:209], v[22:25]
	v_mfma_f32_16x16x32_bf16 v[18:21], v[182:185], v[206:209], v[18:21]
	v_mfma_f32_16x16x32_bf16 v[6:9], v[174:177], v[214:217], v[6:9]
	v_mfma_f32_16x16x32_bf16 v[2:5], v[182:185], v[214:217], v[2:5]
	s_setprio 1
	s_barrier
	s_add_i32 s60, 0, 0x18000
	s_add_i32 s61, 0, 0x1c000
	v_add_u32_e32 v158, s60, v168
	v_add_u32_e32 v182, s61, v168
	ds_read_b128 v[74:77], v158
	ds_read_b128 v[78:81], v158 offset:1024
	ds_read_b128 v[154:157], v158 offset:2048
	ds_read_b128 v[158:161], v158 offset:3072
	ds_read_b128 v[162:165], v182
	ds_read_b128 v[174:177], v182 offset:1024
	ds_read_b128 v[178:181], v182 offset:2048
	ds_read_b128 v[182:185], v182 offset:3072
	s_add_u32 s44, s44, 0x40000
	s_addc_u32 s45, s45, 0
	s_mov_b32 m0, s66
	v_lshl_add_u64 v[224:225], s[44:45], 0, v[138:139]
	ds_read_b128 v[186:189], v172 offset:32768
	ds_read_b128 v[190:193], v172 offset:33792
	ds_read_b128 v[194:197], v172 offset:34816
	ds_read_b128 v[198:201], v172 offset:35840
	ds_read_b128 v[202:205], v172 offset:36864
	ds_read_b128 v[206:209], v172 offset:37888
	ds_read_b128 v[210:213], v172 offset:38912
	ds_read_b128 v[214:217], v172 offset:39936
	global_load_lds_dwordx4 v[224:225], off
	v_lshl_add_u64 v[224:225], s[44:45], 0, v[142:143]
	s_mov_b32 m0, s67
	s_nop 0
	global_load_lds_dwordx4 v[224:225], off
	s_waitcnt vmcnt(8)
	s_waitcnt lgkmcnt(0)
	s_barrier
	s_setprio 0
	s_waitcnt lgkmcnt(0)
	v_mfma_f32_16x16x32_bf16 v[86:89], v[74:77], v[186:189], v[86:89]
	v_mfma_f32_16x16x32_bf16 v[82:85], v[154:157], v[186:189], v[82:85]
	v_mfma_f32_16x16x32_bf16 v[126:129], v[74:77], v[194:197], v[126:129]
	v_mfma_f32_16x16x32_bf16 v[122:125], v[154:157], v[194:197], v[122:125]
	v_mfma_f32_16x16x32_bf16 v[110:113], v[74:77], v[202:205], v[110:113]
	v_mfma_f32_16x16x32_bf16 v[106:109], v[154:157], v[202:205], v[106:109]
	v_mfma_f32_16x16x32_bf16 v[94:97], v[74:77], v[210:213], v[94:97]
	v_mfma_f32_16x16x32_bf16 v[90:93], v[154:157], v[210:213], v[90:93]
	v_mfma_f32_16x16x32_bf16 v[86:89], v[78:81], v[190:193], v[86:89]
	v_mfma_f32_16x16x32_bf16 v[82:85], v[158:161], v[190:193], v[82:85]
	v_mfma_f32_16x16x32_bf16 v[126:129], v[78:81], v[198:201], v[126:129]
	v_mfma_f32_16x16x32_bf16 v[122:125], v[158:161], v[198:201], v[122:125]
	v_mfma_f32_16x16x32_bf16 v[110:113], v[78:81], v[206:209], v[110:113]
	v_mfma_f32_16x16x32_bf16 v[106:109], v[158:161], v[206:209], v[106:109]
	v_mfma_f32_16x16x32_bf16 v[94:97], v[78:81], v[214:217], v[94:97]
	v_mfma_f32_16x16x32_bf16 v[90:93], v[158:161], v[214:217], v[90:93]
	v_mfma_f32_16x16x32_bf16 v[134:137], v[162:165], v[186:189], v[134:137]
	v_mfma_f32_16x16x32_bf16 v[130:133], v[178:181], v[186:189], v[130:133]
	v_mfma_f32_16x16x32_bf16 v[118:121], v[162:165], v[194:197], v[118:121]
	v_mfma_f32_16x16x32_bf16 v[114:117], v[178:181], v[194:197], v[114:117]
	v_mfma_f32_16x16x32_bf16 v[102:105], v[162:165], v[202:205], v[102:105]
	v_mfma_f32_16x16x32_bf16 v[98:101], v[178:181], v[202:205], v[98:101]
	v_mfma_f32_16x16x32_bf16 v[70:73], v[162:165], v[210:213], v[70:73]
	v_mfma_f32_16x16x32_bf16 v[66:69], v[178:181], v[210:213], v[66:69]
	v_mfma_f32_16x16x32_bf16 v[134:137], v[174:177], v[190:193], v[134:137]
	v_mfma_f32_16x16x32_bf16 v[130:133], v[182:185], v[190:193], v[130:133]
	v_mfma_f32_16x16x32_bf16 v[118:121], v[174:177], v[198:201], v[118:121]
	v_mfma_f32_16x16x32_bf16 v[114:117], v[182:185], v[198:201], v[114:117]
	v_mfma_f32_16x16x32_bf16 v[102:105], v[174:177], v[206:209], v[102:105]
	v_mfma_f32_16x16x32_bf16 v[98:101], v[182:185], v[206:209], v[98:101]
	v_mfma_f32_16x16x32_bf16 v[70:73], v[174:177], v[214:217], v[70:73]
	v_mfma_f32_16x16x32_bf16 v[66:69], v[182:185], v[214:217], v[66:69]
	s_setprio 1
	s_barrier
	s_add_i32 s44, s60, s63
	v_lshl_add_u64 v[166:167], v[166:167], 0, s[14:15]
	s_mov_b32 m0, s44
	ds_read_b128 v[186:189], v172 offset:49152
	ds_read_b128 v[190:193], v172 offset:50176
	ds_read_b128 v[194:197], v172 offset:51200
	ds_read_b128 v[198:201], v172 offset:52224
	ds_read_b128 v[202:205], v172 offset:53248
	ds_read_b128 v[206:209], v172 offset:54272
	ds_read_b128 v[210:213], v172 offset:55296
	ds_read_b128 v[214:217], v172 offset:56320
	global_load_lds_dwordx4 v[166:167], off
	s_add_i32 m0, s44, 0x2000
	s_add_u32 s42, s42, 0x40080
	v_lshl_add_u64 v[166:167], v[218:219], 0, s[14:15]
	s_addc_u32 s43, s43, 0
	s_add_i32 s44, s61, s63
	global_load_lds_dwordx4 v[166:167], off
	v_lshl_add_u64 v[166:167], s[42:43], 0, v[140:141]
	s_mov_b32 m0, s44
	s_nop 0
	global_load_lds_dwordx4 v[166:167], off
	v_lshl_add_u64 v[166:167], s[42:43], 0, v[144:145]
	s_add_i32 m0, s44, 0x2000
	s_nop 0
	global_load_lds_dwordx4 v[166:167], off
	v_lshl_add_u64 v[166:167], v[220:221], 0, s[14:15]
	s_mov_b32 m0, s74
	s_nop 0
	global_load_lds_dwordx4 v[166:167], off
	v_lshl_add_u64 v[166:167], v[222:223], 0, s[14:15]
	s_mov_b32 m0, s75
	s_nop 0
	global_load_lds_dwordx4 v[166:167], off
	s_waitcnt vmcnt(8)
	s_waitcnt lgkmcnt(0)
	s_barrier
	s_setprio 0
	s_waitcnt lgkmcnt(0)
	v_mfma_f32_16x16x32_bf16 v[62:65], v[74:77], v[186:189], v[62:65]
	v_mfma_f32_16x16x32_bf16 v[58:61], v[154:157], v[186:189], v[58:61]
	v_mfma_f32_16x16x32_bf16 v[46:49], v[74:77], v[194:197], v[46:49]
	v_mfma_f32_16x16x32_bf16 v[42:45], v[154:157], v[194:197], v[42:45]
	v_mfma_f32_16x16x32_bf16 v[30:33], v[74:77], v[202:205], v[30:33]
	v_mfma_f32_16x16x32_bf16 v[26:29], v[154:157], v[202:205], v[26:29]
	v_mfma_f32_16x16x32_bf16 v[14:17], v[74:77], v[210:213], v[14:17]
	v_mfma_f32_16x16x32_bf16 v[10:13], v[154:157], v[210:213], v[10:13]
	v_mfma_f32_16x16x32_bf16 v[62:65], v[78:81], v[190:193], v[62:65]
	v_mfma_f32_16x16x32_bf16 v[58:61], v[158:161], v[190:193], v[58:61]
	v_mfma_f32_16x16x32_bf16 v[46:49], v[78:81], v[198:201], v[46:49]
	v_mfma_f32_16x16x32_bf16 v[42:45], v[158:161], v[198:201], v[42:45]
	v_mfma_f32_16x16x32_bf16 v[30:33], v[78:81], v[206:209], v[30:33]
	v_mfma_f32_16x16x32_bf16 v[26:29], v[158:161], v[206:209], v[26:29]
	v_mfma_f32_16x16x32_bf16 v[14:17], v[78:81], v[214:217], v[14:17]
	v_mfma_f32_16x16x32_bf16 v[10:13], v[158:161], v[214:217], v[10:13]
	v_mfma_f32_16x16x32_bf16 v[54:57], v[162:165], v[186:189], v[54:57]
	v_mfma_f32_16x16x32_bf16 v[50:53], v[178:181], v[186:189], v[50:53]
	v_mfma_f32_16x16x32_bf16 v[38:41], v[162:165], v[194:197], v[38:41]
	v_mfma_f32_16x16x32_bf16 v[34:37], v[178:181], v[194:197], v[34:37]
	v_mfma_f32_16x16x32_bf16 v[22:25], v[162:165], v[202:205], v[22:25]
	v_mfma_f32_16x16x32_bf16 v[18:21], v[178:181], v[202:205], v[18:21]
	v_mfma_f32_16x16x32_bf16 v[6:9], v[162:165], v[210:213], v[6:9]
	v_mfma_f32_16x16x32_bf16 v[2:5], v[178:181], v[210:213], v[2:5]
	v_mfma_f32_16x16x32_bf16 v[54:57], v[174:177], v[190:193], v[54:57]
	v_mfma_f32_16x16x32_bf16 v[50:53], v[182:185], v[190:193], v[50:53]
	v_mfma_f32_16x16x32_bf16 v[38:41], v[174:177], v[198:201], v[38:41]
	v_mfma_f32_16x16x32_bf16 v[34:37], v[182:185], v[198:201], v[34:37]
	v_mfma_f32_16x16x32_bf16 v[22:25], v[174:177], v[206:209], v[22:25]
	v_mfma_f32_16x16x32_bf16 v[18:21], v[182:185], v[206:209], v[18:21]
	v_mfma_f32_16x16x32_bf16 v[6:9], v[174:177], v[214:217], v[6:9]
	v_mfma_f32_16x16x32_bf16 v[2:5], v[182:185], v[214:217], v[2:5]
	s_setprio 1
	s_barrier
	s_add_i32 s83, s83, 2
	s_add_u32 s40, s40, 0x100
	s_addc_u32 s41, s41, 0
	s_add_u32 s81, s81, 0x100
	s_addc_u32 s82, s82, 0
	s_cmp_gt_u32 s83, 13
	s_cbranch_scc0 .LBB0_493
	s_and_b64 vcc, exec, s[16:17]
	s_cbranch_vccz .LBB0_496
	s_barrier

.LBB0_584:
	ds_read_b128 v[130:133], v166
	ds_read_b128 v[134:137], v166 offset:1024
	ds_read_b128 v[138:141], v166 offset:2048
	ds_read_b128 v[142:145], v166 offset:3072
	ds_read_b128 v[170:173], v167
	ds_read_b128 v[174:177], v167 offset:1024
	ds_read_b128 v[178:181], v167 offset:2048
	ds_read_b128 v[182:185], v167 offset:3072
	s_add_u32 s36, s30, 0xfffc0080
	s_addc_u32 s37, s31, -1
	s_cmp_eq_u32 s75, 12
	s_cselect_b32 s39, s17, s37
	s_cselect_b32 s38, s71, s36
	s_cselect_b32 s37, s15, s74
	s_cselect_b32 s36, s72, s73
	v_lshl_add_u64 v[220:221], s[30:31], 0, v[154:155]
	s_add_i32 m0, s29, 0xc000
	ds_read_b128 v[186:189], v168
	ds_read_b128 v[190:193], v168 offset:1024
	ds_read_b128 v[194:197], v168 offset:2048
	ds_read_b128 v[198:201], v168 offset:3072
	ds_read_b128 v[202:205], v168 offset:4096
	ds_read_b128 v[206:209], v168 offset:5120
	ds_read_b128 v[212:215], v168 offset:6144
	ds_read_b128 v[216:219], v168 offset:7168
	global_load_lds_dwordx4 v[220:221], off
	v_lshl_add_u64 v[220:221], s[30:31], 0, v[156:157]
	s_add_i32 m0, s29, 0xe000
	s_nop 0
	global_load_lds_dwordx4 v[220:221], off
	s_waitcnt vmcnt(8)
	s_waitcnt lgkmcnt(0)
	s_barrier
	s_setprio 0
	s_waitcnt lgkmcnt(0)
	v_mfma_f32_16x16x32_bf16 v[126:129], v[130:133], v[186:189], v[126:129]
	v_mfma_f32_16x16x32_bf16 v[122:125], v[138:141], v[186:189], v[122:125]
	v_mfma_f32_16x16x32_bf16 v[110:113], v[130:133], v[194:197], v[110:113]
	v_mfma_f32_16x16x32_bf16 v[106:109], v[138:141], v[194:197], v[106:109]
	v_mfma_f32_16x16x32_bf16 v[94:97], v[130:133], v[202:205], v[94:97]
	v_mfma_f32_16x16x32_bf16 v[90:93], v[138:141], v[202:205], v[90:93]
	v_mfma_f32_16x16x32_bf16 v[78:81], v[130:133], v[212:215], v[78:81]
	v_mfma_f32_16x16x32_bf16 v[74:77], v[138:141], v[212:215], v[74:77]
	v_mfma_f32_16x16x32_bf16 v[126:129], v[134:137], v[190:193], v[126:129]
	v_mfma_f32_16x16x32_bf16 v[122:125], v[142:145], v[190:193], v[122:125]
	v_mfma_f32_16x16x32_bf16 v[110:113], v[134:137], v[198:201], v[110:113]
	v_mfma_f32_16x16x32_bf16 v[106:109], v[142:145], v[198:201], v[106:109]
	v_mfma_f32_16x16x32_bf16 v[94:97], v[134:137], v[206:209], v[94:97]
	v_mfma_f32_16x16x32_bf16 v[90:93], v[142:145], v[206:209], v[90:93]
	v_mfma_f32_16x16x32_bf16 v[78:81], v[134:137], v[216:219], v[78:81]
	v_mfma_f32_16x16x32_bf16 v[74:77], v[142:145], v[216:219], v[74:77]
	v_mfma_f32_16x16x32_bf16 v[118:121], v[170:173], v[186:189], v[118:121]
	v_mfma_f32_16x16x32_bf16 v[114:117], v[178:181], v[186:189], v[114:117]
	v_mfma_f32_16x16x32_bf16 v[102:105], v[170:173], v[194:197], v[102:105]
	v_mfma_f32_16x16x32_bf16 v[98:101], v[178:181], v[194:197], v[98:101]
	v_mfma_f32_16x16x32_bf16 v[86:89], v[170:173], v[202:205], v[86:89]
	v_mfma_f32_16x16x32_bf16 v[82:85], v[178:181], v[202:205], v[82:85]
	v_mfma_f32_16x16x32_bf16 v[70:73], v[170:173], v[212:215], v[70:73]
	v_mfma_f32_16x16x32_bf16 v[66:69], v[178:181], v[212:215], v[66:69]
	v_mfma_f32_16x16x32_bf16 v[118:121], v[174:177], v[190:193], v[118:121]
	v_mfma_f32_16x16x32_bf16 v[114:117], v[182:185], v[190:193], v[114:117]
	v_mfma_f32_16x16x32_bf16 v[102:105], v[174:177], v[198:201], v[102:105]
	v_mfma_f32_16x16x32_bf16 v[98:101], v[182:185], v[198:201], v[98:101]
	v_mfma_f32_16x16x32_bf16 v[86:89], v[174:177], v[206:209], v[86:89]
	v_mfma_f32_16x16x32_bf16 v[82:85], v[182:185], v[206:209], v[82:85]
	v_mfma_f32_16x16x32_bf16 v[70:73], v[174:177], v[216:219], v[70:73]
	v_mfma_f32_16x16x32_bf16 v[66:69], v[182:185], v[216:219], v[66:69]
	s_setprio 1
	s_barrier
	s_add_i32 s60, s65, s41
	v_lshl_add_u64 v[220:221], s[36:37], 0, v[150:151]
	s_mov_b32 m0, s60
	ds_read_b128 v[186:189], v168 offset:16384
	ds_read_b128 v[190:193], v168 offset:17408
	ds_read_b128 v[194:197], v168 offset:18432
	ds_read_b128 v[198:201], v168 offset:19456
	ds_read_b128 v[202:205], v168 offset:20480
	ds_read_b128 v[206:209], v168 offset:21504
	ds_read_b128 v[212:215], v168 offset:22528
	ds_read_b128 v[216:219], v168 offset:23552
	global_load_lds_dwordx4 v[220:221], off
	s_add_i32 m0, s60, 0x2000
	s_add_u32 s60, s36, 0x40000
	v_lshl_add_u64 v[222:223], s[36:37], 0, v[146:147]
	s_addc_u32 s61, s37, 0
	s_add_i32 s76, s66, s41
	global_load_lds_dwordx4 v[222:223], off
	v_lshl_add_u64 v[224:225], s[60:61], 0, v[150:151]
	s_mov_b32 m0, s76
	v_lshl_add_u64 v[226:227], s[38:39], 0, v[148:149]
	global_load_lds_dwordx4 v[224:225], off
	v_lshl_add_u64 v[224:225], s[60:61], 0, v[146:147]
	s_add_i32 m0, s76, 0x2000
	s_nop 0
	global_load_lds_dwordx4 v[224:225], off
	v_lshl_add_u64 v[224:225], s[38:39], 0, v[152:153]
	s_mov_b32 m0, s29
	s_nop 0
	global_load_lds_dwordx4 v[224:225], off
	s_mov_b32 m0, s45
	s_nop 0
	global_load_lds_dwordx4 v[226:227], off
	s_waitcnt vmcnt(8)
	s_waitcnt lgkmcnt(0)
	s_barrier
	s_setprio 0
	s_waitcnt lgkmcnt(0)
	v_mfma_f32_16x16x32_bf16 v[62:65], v[130:133], v[186:189], v[62:65]
	v_mfma_f32_16x16x32_bf16 v[58:61], v[138:141], v[186:189], v[58:61]
	v_mfma_f32_16x16x32_bf16 v[46:49], v[130:133], v[194:197], v[46:49]
	v_mfma_f32_16x16x32_bf16 v[42:45], v[138:141], v[194:197], v[42:45]
	v_mfma_f32_16x16x32_bf16 v[30:33], v[130:133], v[202:205], v[30:33]
	v_mfma_f32_16x16x32_bf16 v[26:29], v[138:141], v[202:205], v[26:29]
	v_mfma_f32_16x16x32_bf16 v[14:17], v[130:133], v[212:215], v[14:17]
	v_mfma_f32_16x16x32_bf16 v[10:13], v[138:141], v[212:215], v[10:13]
	v_mfma_f32_16x16x32_bf16 v[62:65], v[134:137], v[190:193], v[62:65]
	v_mfma_f32_16x16x32_bf16 v[58:61], v[142:145], v[190:193], v[58:61]
	v_mfma_f32_16x16x32_bf16 v[46:49], v[134:137], v[198:201], v[46:49]
	v_mfma_f32_16x16x32_bf16 v[42:45], v[142:145], v[198:201], v[42:45]
	v_mfma_f32_16x16x32_bf16 v[30:33], v[134:137], v[206:209], v[30:33]
	v_mfma_f32_16x16x32_bf16 v[26:29], v[142:145], v[206:209], v[26:29]
	v_mfma_f32_16x16x32_bf16 v[14:17], v[134:137], v[216:219], v[14:17]
	v_mfma_f32_16x16x32_bf16 v[10:13], v[142:145], v[216:219], v[10:13]
	v_mfma_f32_16x16x32_bf16 v[54:57], v[170:173], v[186:189], v[54:57]
	v_mfma_f32_16x16x32_bf16 v[50:53], v[178:181], v[186:189], v[50:53]
	v_mfma_f32_16x16x32_bf16 v[38:41], v[170:173], v[194:197], v[38:41]
	v_mfma_f32_16x16x32_bf16 v[34:37], v[178:181], v[194:197], v[34:37]
	v_mfma_f32_16x16x32_bf16 v[22:25], v[170:173], v[202:205], v[22:25]
	v_mfma_f32_16x16x32_bf16 v[18:21], v[178:181], v[202:205], v[18:21]
	v_mfma_f32_16x16x32_bf16 v[6:9], v[170:173], v[212:215], v[6:9]
	v_mfma_f32_16x16x32_bf16 v[2:5], v[178:181], v[212:215], v[2:5]
	v_mfma_f32_16x16x32_bf16 v[54:57], v[174:177], v[190:193], v[54:57]
	v_mfma_f32_16x16x32_bf16 v[50:53], v[182:185], v[190:193], v[50:53]
	v_mfma_f32_16x16x32_bf16 v[38:41], v[174:177], v[198:201], v[38:41]
	v_mfma_f32_16x16x32_bf16 v[34:37], v[182:185], v[198:201], v[34:37]
	v_mfma_f32_16x16x32_bf16 v[22:25], v[174:177], v[206:209], v[22:25]
	v_mfma_f32_16x16x32_bf16 v[18:21], v[182:185], v[206:209], v[18:21]
	v_mfma_f32_16x16x32_bf16 v[6:9], v[174:177], v[216:219], v[6:9]
	v_mfma_f32_16x16x32_bf16 v[2:5], v[182:185], v[216:219], v[2:5]
	s_setprio 1
	s_barrier
	s_add_i32 s60, 0, 0x18000
	s_add_i32 s61, 0, 0x1c000
	v_add_u32_e32 v142, s60, v164
	v_add_u32_e32 v169, s61, v164
	ds_read_b128 v[130:133], v142
	ds_read_b128 v[134:137], v142 offset:1024
	ds_read_b128 v[138:141], v142 offset:2048
	ds_read_b128 v[142:145], v142 offset:3072
	ds_read_b128 v[170:173], v169
	ds_read_b128 v[174:177], v169 offset:1024
	ds_read_b128 v[178:181], v169 offset:2048
	ds_read_b128 v[182:185], v169 offset:3072
	s_add_u32 s38, s38, 0x40000
	s_addc_u32 s39, s39, 0
	s_mov_b32 m0, s46
	v_lshl_add_u64 v[228:229], s[38:39], 0, v[152:153]
	ds_read_b128 v[186:189], v168 offset:32768
	ds_read_b128 v[190:193], v168 offset:33792
	ds_read_b128 v[194:197], v168 offset:34816
	ds_read_b128 v[198:201], v168 offset:35840
	ds_read_b128 v[202:205], v168 offset:36864
	ds_read_b128 v[206:209], v168 offset:37888
	ds_read_b128 v[212:215], v168 offset:38912
	ds_read_b128 v[216:219], v168 offset:39936
	global_load_lds_dwordx4 v[228:229], off
	v_lshl_add_u64 v[228:229], s[38:39], 0, v[148:149]
	s_mov_b32 m0, s47
	s_nop 0
	global_load_lds_dwordx4 v[228:229], off
	s_waitcnt vmcnt(8)
	s_waitcnt lgkmcnt(0)
	s_barrier
	s_setprio 0
	s_waitcnt lgkmcnt(0)
	v_mfma_f32_16x16x32_bf16 v[126:129], v[130:133], v[186:189], v[126:129]
	v_mfma_f32_16x16x32_bf16 v[122:125], v[138:141], v[186:189], v[122:125]
	v_mfma_f32_16x16x32_bf16 v[110:113], v[130:133], v[194:197], v[110:113]
	v_mfma_f32_16x16x32_bf16 v[106:109], v[138:141], v[194:197], v[106:109]
	v_mfma_f32_16x16x32_bf16 v[94:97], v[130:133], v[202:205], v[94:97]
	v_mfma_f32_16x16x32_bf16 v[90:93], v[138:141], v[202:205], v[90:93]
	v_mfma_f32_16x16x32_bf16 v[78:81], v[130:133], v[212:215], v[78:81]
	v_mfma_f32_16x16x32_bf16 v[74:77], v[138:141], v[212:215], v[74:77]
	v_mfma_f32_16x16x32_bf16 v[126:129], v[134:137], v[190:193], v[126:129]
	v_mfma_f32_16x16x32_bf16 v[122:125], v[142:145], v[190:193], v[122:125]
	v_mfma_f32_16x16x32_bf16 v[110:113], v[134:137], v[198:201], v[110:113]
	v_mfma_f32_16x16x32_bf16 v[106:109], v[142:145], v[198:201], v[106:109]
	v_mfma_f32_16x16x32_bf16 v[94:97], v[134:137], v[206:209], v[94:97]
	v_mfma_f32_16x16x32_bf16 v[90:93], v[142:145], v[206:209], v[90:93]
	v_mfma_f32_16x16x32_bf16 v[78:81], v[134:137], v[216:219], v[78:81]
	v_mfma_f32_16x16x32_bf16 v[74:77], v[142:145], v[216:219], v[74:77]
	v_mfma_f32_16x16x32_bf16 v[118:121], v[170:173], v[186:189], v[118:121]
	v_mfma_f32_16x16x32_bf16 v[114:117], v[178:181], v[186:189], v[114:117]
	v_mfma_f32_16x16x32_bf16 v[102:105], v[170:173], v[194:197], v[102:105]
	v_mfma_f32_16x16x32_bf16 v[98:101], v[178:181], v[194:197], v[98:101]
	v_mfma_f32_16x16x32_bf16 v[86:89], v[170:173], v[202:205], v[86:89]
	v_mfma_f32_16x16x32_bf16 v[82:85], v[178:181], v[202:205], v[82:85]
	v_mfma_f32_16x16x32_bf16 v[70:73], v[170:173], v[212:215], v[70:73]
	v_mfma_f32_16x16x32_bf16 v[66:69], v[178:181], v[212:215], v[66:69]
	v_mfma_f32_16x16x32_bf16 v[118:121], v[174:177], v[190:193], v[118:121]
	v_mfma_f32_16x16x32_bf16 v[114:117], v[182:185], v[190:193], v[114:117]
	v_mfma_f32_16x16x32_bf16 v[102:105], v[174:177], v[198:201], v[102:105]
	v_mfma_f32_16x16x32_bf16 v[98:101], v[182:185], v[198:201], v[98:101]
	v_mfma_f32_16x16x32_bf16 v[86:89], v[174:177], v[206:209], v[86:89]
	v_mfma_f32_16x16x32_bf16 v[82:85], v[182:185], v[206:209], v[82:85]
	v_mfma_f32_16x16x32_bf16 v[70:73], v[174:177], v[216:219], v[70:73]
	v_mfma_f32_16x16x32_bf16 v[66:69], v[182:185], v[216:219], v[66:69]
	s_setprio 1
	s_barrier
	s_add_i32 s38, s60, s41
	v_lshl_add_u64 v[220:221], v[220:221], 0, s[10:11]
	s_mov_b32 m0, s38
	ds_read_b128 v[186:189], v168 offset:49152
	ds_read_b128 v[190:193], v168 offset:50176
	ds_read_b128 v[194:197], v168 offset:51200
	ds_read_b128 v[198:201], v168 offset:52224
	ds_read_b128 v[202:205], v168 offset:53248
	ds_read_b128 v[206:209], v168 offset:54272
	ds_read_b128 v[212:215], v168 offset:55296
	ds_read_b128 v[216:219], v168 offset:56320
	global_load_lds_dwordx4 v[220:221], off
	s_add_i32 m0, s38, 0x2000
	s_add_u32 s36, s36, 0x40080
	v_lshl_add_u64 v[220:221], v[222:223], 0, s[10:11]
	s_addc_u32 s37, s37, 0
	s_add_i32 s38, s61, s41
	global_load_lds_dwordx4 v[220:221], off
	v_lshl_add_u64 v[220:221], s[36:37], 0, v[150:151]
	s_mov_b32 m0, s38
	s_nop 0
	global_load_lds_dwordx4 v[220:221], off
	v_lshl_add_u64 v[220:221], s[36:37], 0, v[146:147]
	s_add_i32 m0, s38, 0x2000
	s_nop 0
	global_load_lds_dwordx4 v[220:221], off
	v_lshl_add_u64 v[220:221], v[224:225], 0, s[10:11]
	s_mov_b32 m0, s63
	s_nop 0
	global_load_lds_dwordx4 v[220:221], off
	v_lshl_add_u64 v[220:221], v[226:227], 0, s[10:11]
	s_mov_b32 m0, s64
	s_nop 0
	global_load_lds_dwordx4 v[220:221], off
	s_waitcnt vmcnt(8)
	s_waitcnt lgkmcnt(0)
	s_barrier
	s_setprio 0
	s_waitcnt lgkmcnt(0)
	v_mfma_f32_16x16x32_bf16 v[62:65], v[130:133], v[186:189], v[62:65]
	v_mfma_f32_16x16x32_bf16 v[58:61], v[138:141], v[186:189], v[58:61]
	v_mfma_f32_16x16x32_bf16 v[46:49], v[130:133], v[194:197], v[46:49]
	v_mfma_f32_16x16x32_bf16 v[42:45], v[138:141], v[194:197], v[42:45]
	v_mfma_f32_16x16x32_bf16 v[30:33], v[130:133], v[202:205], v[30:33]
	v_mfma_f32_16x16x32_bf16 v[26:29], v[138:141], v[202:205], v[26:29]
	v_mfma_f32_16x16x32_bf16 v[14:17], v[130:133], v[212:215], v[14:17]
	v_mfma_f32_16x16x32_bf16 v[10:13], v[138:141], v[212:215], v[10:13]
	v_mfma_f32_16x16x32_bf16 v[62:65], v[134:137], v[190:193], v[62:65]
	v_mfma_f32_16x16x32_bf16 v[58:61], v[142:145], v[190:193], v[58:61]
	v_mfma_f32_16x16x32_bf16 v[46:49], v[134:137], v[198:201], v[46:49]
	v_mfma_f32_16x16x32_bf16 v[42:45], v[142:145], v[198:201], v[42:45]
	v_mfma_f32_16x16x32_bf16 v[30:33], v[134:137], v[206:209], v[30:33]
	v_mfma_f32_16x16x32_bf16 v[26:29], v[142:145], v[206:209], v[26:29]
	v_mfma_f32_16x16x32_bf16 v[14:17], v[134:137], v[216:219], v[14:17]
	v_mfma_f32_16x16x32_bf16 v[10:13], v[142:145], v[216:219], v[10:13]
	v_mfma_f32_16x16x32_bf16 v[54:57], v[170:173], v[186:189], v[54:57]
	v_mfma_f32_16x16x32_bf16 v[50:53], v[178:181], v[186:189], v[50:53]
	v_mfma_f32_16x16x32_bf16 v[38:41], v[170:173], v[194:197], v[38:41]
	v_mfma_f32_16x16x32_bf16 v[34:37], v[178:181], v[194:197], v[34:37]
	v_mfma_f32_16x16x32_bf16 v[22:25], v[170:173], v[202:205], v[22:25]
	v_mfma_f32_16x16x32_bf16 v[18:21], v[178:181], v[202:205], v[18:21]
	v_mfma_f32_16x16x32_bf16 v[6:9], v[170:173], v[212:215], v[6:9]
	v_mfma_f32_16x16x32_bf16 v[2:5], v[178:181], v[212:215], v[2:5]
	v_mfma_f32_16x16x32_bf16 v[54:57], v[174:177], v[190:193], v[54:57]
	v_mfma_f32_16x16x32_bf16 v[50:53], v[182:185], v[190:193], v[50:53]
	v_mfma_f32_16x16x32_bf16 v[38:41], v[174:177], v[198:201], v[38:41]
	v_mfma_f32_16x16x32_bf16 v[34:37], v[182:185], v[198:201], v[34:37]
	v_mfma_f32_16x16x32_bf16 v[22:25], v[174:177], v[206:209], v[22:25]
	v_mfma_f32_16x16x32_bf16 v[18:21], v[182:185], v[206:209], v[18:21]
	v_mfma_f32_16x16x32_bf16 v[6:9], v[174:177], v[216:219], v[6:9]
	v_mfma_f32_16x16x32_bf16 v[2:5], v[182:185], v[216:219], v[2:5]
	s_setprio 1
	s_barrier
	s_add_i32 s75, s75, 2
	s_add_u32 s30, s30, 0x100
	s_addc_u32 s31, s31, 0
	s_add_u32 s73, s73, 0x100
	s_addc_u32 s74, s74, 0
	s_cmp_gt_u32 s75, 13
	s_cbranch_scc0 .LBB0_584
	s_and_b64 vcc, exec, s[12:13]
	s_cbranch_vccz .LBB0_587
	s_barrier

.LBB0_665:
	ds_read_b128 v[82:85], v169
	ds_read_b128 v[86:89], v169 offset:1024
	ds_read_b128 v[90:93], v169 offset:2048
	ds_read_b128 v[94:97], v169 offset:3072
	ds_read_b128 v[162:165], v170
	ds_read_b128 v[174:177], v170 offset:1024
	ds_read_b128 v[178:181], v170 offset:2048
	ds_read_b128 v[182:185], v170 offset:3072
	s_add_u32 s30, s28, 0xfff50080
	s_addc_u32 s31, s29, -1
	s_cmp_eq_u32 s75, 40
	s_cselect_b32 s37, s7, s31
	s_cselect_b32 s36, s6, s30
	s_cselect_b32 s31, s25, s74
	s_cselect_b32 s30, s24, s73
	v_lshl_add_u64 v[220:221], s[28:29], 0, v[154:155]
	s_add_i32 m0, s42, 0xc000
	ds_read_b128 v[186:189], v171
	ds_read_b128 v[190:193], v171 offset:1024
	ds_read_b128 v[194:197], v171 offset:2048
	ds_read_b128 v[198:201], v171 offset:3072
	ds_read_b128 v[202:205], v171 offset:4096
	ds_read_b128 v[206:209], v171 offset:5120
	ds_read_b128 v[212:215], v171 offset:6144
	ds_read_b128 v[216:219], v171 offset:7168
	global_load_lds_dwordx4 v[220:221], off
	v_lshl_add_u64 v[220:221], s[28:29], 0, v[156:157]
	s_add_i32 m0, s42, 0xe000
	s_nop 0
	global_load_lds_dwordx4 v[220:221], off
	s_waitcnt vmcnt(8)
	s_waitcnt lgkmcnt(0)
	s_barrier
	s_setprio 0
	s_waitcnt lgkmcnt(0)
	v_mfma_f32_16x16x32_bf16 v[142:145], v[82:85], v[186:189], v[142:145]
	v_mfma_f32_16x16x32_bf16 v[138:141], v[90:93], v[186:189], v[138:141]
	v_mfma_f32_16x16x32_bf16 v[126:129], v[82:85], v[194:197], v[126:129]
	v_mfma_f32_16x16x32_bf16 v[122:125], v[90:93], v[194:197], v[122:125]
	v_mfma_f32_16x16x32_bf16 v[110:113], v[82:85], v[202:205], v[110:113]
	v_mfma_f32_16x16x32_bf16 v[106:109], v[90:93], v[202:205], v[106:109]
	v_mfma_f32_16x16x32_bf16 v[78:81], v[82:85], v[212:215], v[78:81]
	v_mfma_f32_16x16x32_bf16 v[74:77], v[90:93], v[212:215], v[74:77]
	v_mfma_f32_16x16x32_bf16 v[142:145], v[86:89], v[190:193], v[142:145]
	v_mfma_f32_16x16x32_bf16 v[138:141], v[94:97], v[190:193], v[138:141]
	v_mfma_f32_16x16x32_bf16 v[126:129], v[86:89], v[198:201], v[126:129]
	v_mfma_f32_16x16x32_bf16 v[122:125], v[94:97], v[198:201], v[122:125]
	v_mfma_f32_16x16x32_bf16 v[110:113], v[86:89], v[206:209], v[110:113]
	v_mfma_f32_16x16x32_bf16 v[106:109], v[94:97], v[206:209], v[106:109]
	v_mfma_f32_16x16x32_bf16 v[78:81], v[86:89], v[216:219], v[78:81]
	v_mfma_f32_16x16x32_bf16 v[74:77], v[94:97], v[216:219], v[74:77]
	v_mfma_f32_16x16x32_bf16 v[134:137], v[162:165], v[186:189], v[134:137]
	v_mfma_f32_16x16x32_bf16 v[130:133], v[178:181], v[186:189], v[130:133]
	v_mfma_f32_16x16x32_bf16 v[118:121], v[162:165], v[194:197], v[118:121]
	v_mfma_f32_16x16x32_bf16 v[114:117], v[178:181], v[194:197], v[114:117]
	v_mfma_f32_16x16x32_bf16 v[102:105], v[162:165], v[202:205], v[102:105]
	v_mfma_f32_16x16x32_bf16 v[98:101], v[178:181], v[202:205], v[98:101]
	v_mfma_f32_16x16x32_bf16 v[70:73], v[162:165], v[212:215], v[70:73]
	v_mfma_f32_16x16x32_bf16 v[66:69], v[178:181], v[212:215], v[66:69]
	v_mfma_f32_16x16x32_bf16 v[134:137], v[174:177], v[190:193], v[134:137]
	v_mfma_f32_16x16x32_bf16 v[130:133], v[182:185], v[190:193], v[130:133]
	v_mfma_f32_16x16x32_bf16 v[118:121], v[174:177], v[198:201], v[118:121]
	v_mfma_f32_16x16x32_bf16 v[114:117], v[182:185], v[198:201], v[114:117]
	v_mfma_f32_16x16x32_bf16 v[102:105], v[174:177], v[206:209], v[102:105]
	v_mfma_f32_16x16x32_bf16 v[98:101], v[182:185], v[206:209], v[98:101]
	v_mfma_f32_16x16x32_bf16 v[70:73], v[174:177], v[216:219], v[70:73]
	v_mfma_f32_16x16x32_bf16 v[66:69], v[182:185], v[216:219], v[66:69]
	s_setprio 1
	s_barrier
	s_add_i32 s60, s67, s41
	v_lshl_add_u64 v[220:221], s[30:31], 0, v[148:149]
	s_mov_b32 m0, s60
	ds_read_b128 v[186:189], v171 offset:16384
	ds_read_b128 v[190:193], v171 offset:17408
	ds_read_b128 v[194:197], v171 offset:18432
	ds_read_b128 v[198:201], v171 offset:19456
	ds_read_b128 v[202:205], v171 offset:20480
	ds_read_b128 v[206:209], v171 offset:21504
	ds_read_b128 v[212:215], v171 offset:22528
	ds_read_b128 v[216:219], v171 offset:23552
	global_load_lds_dwordx4 v[220:221], off
	s_add_i32 m0, s60, 0x2000
	s_add_u32 s60, s30, 0xb0000
	v_lshl_add_u64 v[222:223], s[30:31], 0, v[152:153]
	s_addc_u32 s61, s31, 0
	s_add_i32 s76, s68, s41
	global_load_lds_dwordx4 v[222:223], off
	v_lshl_add_u64 v[224:225], s[60:61], 0, v[148:149]
	s_mov_b32 m0, s76
	v_lshl_add_u64 v[226:227], s[36:37], 0, v[150:151]
	global_load_lds_dwordx4 v[224:225], off
	v_lshl_add_u64 v[224:225], s[60:61], 0, v[152:153]
	s_add_i32 m0, s76, 0x2000
	s_nop 0
	global_load_lds_dwordx4 v[224:225], off
	v_lshl_add_u64 v[224:225], s[36:37], 0, v[146:147]
	s_mov_b32 m0, s42
	s_nop 0
	global_load_lds_dwordx4 v[224:225], off
	s_mov_b32 m0, s43
	s_nop 0
	global_load_lds_dwordx4 v[226:227], off
	s_waitcnt vmcnt(8)
	s_waitcnt lgkmcnt(0)
	s_barrier
	s_setprio 0
	s_waitcnt lgkmcnt(0)
	v_mfma_f32_16x16x32_bf16 v[62:65], v[82:85], v[186:189], v[62:65]
	v_mfma_f32_16x16x32_bf16 v[58:61], v[90:93], v[186:189], v[58:61]
	v_mfma_f32_16x16x32_bf16 v[46:49], v[82:85], v[194:197], v[46:49]
	v_mfma_f32_16x16x32_bf16 v[42:45], v[90:93], v[194:197], v[42:45]
	v_mfma_f32_16x16x32_bf16 v[30:33], v[82:85], v[202:205], v[30:33]
	v_mfma_f32_16x16x32_bf16 v[26:29], v[90:93], v[202:205], v[26:29]
	v_mfma_f32_16x16x32_bf16 v[14:17], v[82:85], v[212:215], v[14:17]
	v_mfma_f32_16x16x32_bf16 v[10:13], v[90:93], v[212:215], v[10:13]
	v_mfma_f32_16x16x32_bf16 v[62:65], v[86:89], v[190:193], v[62:65]
	v_mfma_f32_16x16x32_bf16 v[58:61], v[94:97], v[190:193], v[58:61]
	v_mfma_f32_16x16x32_bf16 v[46:49], v[86:89], v[198:201], v[46:49]
	v_mfma_f32_16x16x32_bf16 v[42:45], v[94:97], v[198:201], v[42:45]
	v_mfma_f32_16x16x32_bf16 v[30:33], v[86:89], v[206:209], v[30:33]
	v_mfma_f32_16x16x32_bf16 v[26:29], v[94:97], v[206:209], v[26:29]
	v_mfma_f32_16x16x32_bf16 v[14:17], v[86:89], v[216:219], v[14:17]
	v_mfma_f32_16x16x32_bf16 v[10:13], v[94:97], v[216:219], v[10:13]
	v_mfma_f32_16x16x32_bf16 v[54:57], v[162:165], v[186:189], v[54:57]
	v_mfma_f32_16x16x32_bf16 v[50:53], v[178:181], v[186:189], v[50:53]
	v_mfma_f32_16x16x32_bf16 v[38:41], v[162:165], v[194:197], v[38:41]
	v_mfma_f32_16x16x32_bf16 v[34:37], v[178:181], v[194:197], v[34:37]
	v_mfma_f32_16x16x32_bf16 v[22:25], v[162:165], v[202:205], v[22:25]
	v_mfma_f32_16x16x32_bf16 v[18:21], v[178:181], v[202:205], v[18:21]
	v_mfma_f32_16x16x32_bf16 v[6:9], v[162:165], v[212:215], v[6:9]
	v_mfma_f32_16x16x32_bf16 v[2:5], v[178:181], v[212:215], v[2:5]
	v_mfma_f32_16x16x32_bf16 v[54:57], v[174:177], v[190:193], v[54:57]
	v_mfma_f32_16x16x32_bf16 v[50:53], v[182:185], v[190:193], v[50:53]
	v_mfma_f32_16x16x32_bf16 v[38:41], v[174:177], v[198:201], v[38:41]
	v_mfma_f32_16x16x32_bf16 v[34:37], v[182:185], v[198:201], v[34:37]
	v_mfma_f32_16x16x32_bf16 v[22:25], v[174:177], v[206:209], v[22:25]
	v_mfma_f32_16x16x32_bf16 v[18:21], v[182:185], v[206:209], v[18:21]
	v_mfma_f32_16x16x32_bf16 v[6:9], v[174:177], v[216:219], v[6:9]
	v_mfma_f32_16x16x32_bf16 v[2:5], v[182:185], v[216:219], v[2:5]
	s_setprio 1
	s_barrier
	s_add_i32 s60, 0, 0x18000
	s_add_i32 s61, 0, 0x1c000
	v_add_u32_e32 v94, s60, v167
	v_add_u32_e32 v173, s61, v167
	ds_read_b128 v[82:85], v94
	ds_read_b128 v[86:89], v94 offset:1024
	ds_read_b128 v[90:93], v94 offset:2048
	ds_read_b128 v[94:97], v94 offset:3072
	ds_read_b128 v[162:165], v173
	ds_read_b128 v[174:177], v173 offset:1024
	ds_read_b128 v[178:181], v173 offset:2048
	ds_read_b128 v[182:185], v173 offset:3072
	s_add_u32 s36, s36, 0xb0000
	s_addc_u32 s37, s37, 0
	s_mov_b32 m0, s44
	v_lshl_add_u64 v[228:229], s[36:37], 0, v[146:147]
	ds_read_b128 v[186:189], v171 offset:32768
	ds_read_b128 v[190:193], v171 offset:33792
	ds_read_b128 v[194:197], v171 offset:34816
	ds_read_b128 v[198:201], v171 offset:35840
	ds_read_b128 v[202:205], v171 offset:36864
	ds_read_b128 v[206:209], v171 offset:37888
	ds_read_b128 v[212:215], v171 offset:38912
	ds_read_b128 v[216:219], v171 offset:39936
	global_load_lds_dwordx4 v[228:229], off
	v_lshl_add_u64 v[228:229], s[36:37], 0, v[150:151]
	s_mov_b32 m0, s45
	s_nop 0
	global_load_lds_dwordx4 v[228:229], off
	s_waitcnt vmcnt(8)
	s_waitcnt lgkmcnt(0)
	s_barrier
	s_setprio 0
	s_waitcnt lgkmcnt(0)
	v_mfma_f32_16x16x32_bf16 v[142:145], v[82:85], v[186:189], v[142:145]
	v_mfma_f32_16x16x32_bf16 v[138:141], v[90:93], v[186:189], v[138:141]
	v_mfma_f32_16x16x32_bf16 v[126:129], v[82:85], v[194:197], v[126:129]
	v_mfma_f32_16x16x32_bf16 v[122:125], v[90:93], v[194:197], v[122:125]
	v_mfma_f32_16x16x32_bf16 v[110:113], v[82:85], v[202:205], v[110:113]
	v_mfma_f32_16x16x32_bf16 v[106:109], v[90:93], v[202:205], v[106:109]
	v_mfma_f32_16x16x32_bf16 v[78:81], v[82:85], v[212:215], v[78:81]
	v_mfma_f32_16x16x32_bf16 v[74:77], v[90:93], v[212:215], v[74:77]
	v_mfma_f32_16x16x32_bf16 v[142:145], v[86:89], v[190:193], v[142:145]
	v_mfma_f32_16x16x32_bf16 v[138:141], v[94:97], v[190:193], v[138:141]
	v_mfma_f32_16x16x32_bf16 v[126:129], v[86:89], v[198:201], v[126:129]
	v_mfma_f32_16x16x32_bf16 v[122:125], v[94:97], v[198:201], v[122:125]
	v_mfma_f32_16x16x32_bf16 v[110:113], v[86:89], v[206:209], v[110:113]
	v_mfma_f32_16x16x32_bf16 v[106:109], v[94:97], v[206:209], v[106:109]
	v_mfma_f32_16x16x32_bf16 v[78:81], v[86:89], v[216:219], v[78:81]
	v_mfma_f32_16x16x32_bf16 v[74:77], v[94:97], v[216:219], v[74:77]
	v_mfma_f32_16x16x32_bf16 v[134:137], v[162:165], v[186:189], v[134:137]
	v_mfma_f32_16x16x32_bf16 v[130:133], v[178:181], v[186:189], v[130:133]
	v_mfma_f32_16x16x32_bf16 v[118:121], v[162:165], v[194:197], v[118:121]
	v_mfma_f32_16x16x32_bf16 v[114:117], v[178:181], v[194:197], v[114:117]
	v_mfma_f32_16x16x32_bf16 v[102:105], v[162:165], v[202:205], v[102:105]
	v_mfma_f32_16x16x32_bf16 v[98:101], v[178:181], v[202:205], v[98:101]
	v_mfma_f32_16x16x32_bf16 v[70:73], v[162:165], v[212:215], v[70:73]
	v_mfma_f32_16x16x32_bf16 v[66:69], v[178:181], v[212:215], v[66:69]
	v_mfma_f32_16x16x32_bf16 v[134:137], v[174:177], v[190:193], v[134:137]
	v_mfma_f32_16x16x32_bf16 v[130:133], v[182:185], v[190:193], v[130:133]
	v_mfma_f32_16x16x32_bf16 v[118:121], v[174:177], v[198:201], v[118:121]
	v_mfma_f32_16x16x32_bf16 v[114:117], v[182:185], v[198:201], v[114:117]
	v_mfma_f32_16x16x32_bf16 v[102:105], v[174:177], v[206:209], v[102:105]
	v_mfma_f32_16x16x32_bf16 v[98:101], v[182:185], v[206:209], v[98:101]
	v_mfma_f32_16x16x32_bf16 v[70:73], v[174:177], v[216:219], v[70:73]
	v_mfma_f32_16x16x32_bf16 v[66:69], v[182:185], v[216:219], v[66:69]
	s_setprio 1
	s_barrier
	s_add_i32 s36, s60, s41
	v_lshl_add_u64 v[220:221], v[220:221], 0, s[16:17]
	s_mov_b32 m0, s36
	ds_read_b128 v[186:189], v171 offset:49152
	ds_read_b128 v[190:193], v171 offset:50176
	ds_read_b128 v[194:197], v171 offset:51200
	ds_read_b128 v[198:201], v171 offset:52224
	ds_read_b128 v[202:205], v171 offset:53248
	ds_read_b128 v[206:209], v171 offset:54272
	ds_read_b128 v[212:215], v171 offset:55296
	ds_read_b128 v[216:219], v171 offset:56320
	global_load_lds_dwordx4 v[220:221], off
	s_add_i32 m0, s36, 0x2000
	s_add_u32 s30, s30, 0xb0080
	v_lshl_add_u64 v[220:221], v[222:223], 0, s[16:17]
	s_addc_u32 s31, s31, 0
	s_add_i32 s36, s61, s41
	global_load_lds_dwordx4 v[220:221], off
	v_lshl_add_u64 v[220:221], s[30:31], 0, v[148:149]
	s_mov_b32 m0, s36
	s_nop 0
	global_load_lds_dwordx4 v[220:221], off
	v_lshl_add_u64 v[220:221], s[30:31], 0, v[152:153]
	s_add_i32 m0, s36, 0x2000
	s_nop 0
	global_load_lds_dwordx4 v[220:221], off
	v_lshl_add_u64 v[220:221], v[224:225], 0, s[16:17]
	s_mov_b32 m0, s64
	s_nop 0
	global_load_lds_dwordx4 v[220:221], off
	v_lshl_add_u64 v[220:221], v[226:227], 0, s[16:17]
	s_mov_b32 m0, s65
	s_nop 0
	global_load_lds_dwordx4 v[220:221], off
	s_waitcnt vmcnt(8)
	s_waitcnt lgkmcnt(0)
	s_barrier
	s_setprio 0
	s_waitcnt lgkmcnt(0)
	v_mfma_f32_16x16x32_bf16 v[62:65], v[82:85], v[186:189], v[62:65]
	v_mfma_f32_16x16x32_bf16 v[58:61], v[90:93], v[186:189], v[58:61]
	v_mfma_f32_16x16x32_bf16 v[46:49], v[82:85], v[194:197], v[46:49]
	v_mfma_f32_16x16x32_bf16 v[42:45], v[90:93], v[194:197], v[42:45]
	v_mfma_f32_16x16x32_bf16 v[30:33], v[82:85], v[202:205], v[30:33]
	v_mfma_f32_16x16x32_bf16 v[26:29], v[90:93], v[202:205], v[26:29]
	v_mfma_f32_16x16x32_bf16 v[14:17], v[82:85], v[212:215], v[14:17]
	v_mfma_f32_16x16x32_bf16 v[10:13], v[90:93], v[212:215], v[10:13]
	v_mfma_f32_16x16x32_bf16 v[62:65], v[86:89], v[190:193], v[62:65]
	v_mfma_f32_16x16x32_bf16 v[58:61], v[94:97], v[190:193], v[58:61]
	v_mfma_f32_16x16x32_bf16 v[46:49], v[86:89], v[198:201], v[46:49]
	v_mfma_f32_16x16x32_bf16 v[42:45], v[94:97], v[198:201], v[42:45]
	v_mfma_f32_16x16x32_bf16 v[30:33], v[86:89], v[206:209], v[30:33]
	v_mfma_f32_16x16x32_bf16 v[26:29], v[94:97], v[206:209], v[26:29]
	v_mfma_f32_16x16x32_bf16 v[14:17], v[86:89], v[216:219], v[14:17]
	v_mfma_f32_16x16x32_bf16 v[10:13], v[94:97], v[216:219], v[10:13]
	v_mfma_f32_16x16x32_bf16 v[54:57], v[162:165], v[186:189], v[54:57]
	v_mfma_f32_16x16x32_bf16 v[50:53], v[178:181], v[186:189], v[50:53]
	v_mfma_f32_16x16x32_bf16 v[38:41], v[162:165], v[194:197], v[38:41]
	v_mfma_f32_16x16x32_bf16 v[34:37], v[178:181], v[194:197], v[34:37]
	v_mfma_f32_16x16x32_bf16 v[22:25], v[162:165], v[202:205], v[22:25]
	v_mfma_f32_16x16x32_bf16 v[18:21], v[178:181], v[202:205], v[18:21]
	v_mfma_f32_16x16x32_bf16 v[6:9], v[162:165], v[212:215], v[6:9]
	v_mfma_f32_16x16x32_bf16 v[2:5], v[178:181], v[212:215], v[2:5]
	v_mfma_f32_16x16x32_bf16 v[54:57], v[174:177], v[190:193], v[54:57]
	v_mfma_f32_16x16x32_bf16 v[50:53], v[182:185], v[190:193], v[50:53]
	v_mfma_f32_16x16x32_bf16 v[38:41], v[174:177], v[198:201], v[38:41]
	v_mfma_f32_16x16x32_bf16 v[34:37], v[182:185], v[198:201], v[34:37]
	v_mfma_f32_16x16x32_bf16 v[22:25], v[174:177], v[206:209], v[22:25]
	v_mfma_f32_16x16x32_bf16 v[18:21], v[182:185], v[206:209], v[18:21]
	v_mfma_f32_16x16x32_bf16 v[6:9], v[174:177], v[216:219], v[6:9]
	v_mfma_f32_16x16x32_bf16 v[2:5], v[182:185], v[216:219], v[2:5]
	s_setprio 1
	s_barrier
	s_add_i32 s75, s75, 2
	s_add_u32 s28, s28, 0x100
	s_addc_u32 s29, s29, 0
	s_add_u32 s73, s73, 0x100
	s_addc_u32 s74, s74, 0
	s_cmp_gt_u32 s75, 41
	s_cbranch_scc0 .LBB0_665
	s_and_b64 vcc, exec, s[18:19]
	s_cbranch_vccz .LBB0_668
	s_barrier

.LBB0_911:
	ds_read_b128 v[156:159], v153
	ds_read_b128 v[160:163], v153 offset:1024
	ds_read_b128 v[164:167], v153 offset:2048
	ds_read_b128 v[168:171], v153 offset:3072
	ds_read_b128 v[172:175], v154
	ds_read_b128 v[176:179], v154 offset:1024
	ds_read_b128 v[180:183], v154 offset:2048
	ds_read_b128 v[184:187], v154 offset:3072
	s_add_u32 s42, s40, 0x100
	s_addc_u32 s43, s41, 0
	s_add_u32 s44, s77, s40
	s_addc_u32 s45, s78, s41
	s_cmp_eq_u32 s79, 4
	s_cselect_b32 s46, s37, s44
	s_cselect_b32 s44, 0, s42
	s_cselect_b32 s47, s31, s45
	s_cselect_b32 s45, 0, s43
	s_add_u32 s44, s6, s44
	s_addc_u32 s45, s7, s45
	v_lshl_add_u64 v[208:209], v[146:147], 0, s[40:41]
	s_add_i32 m0, s29, 0xc000
	ds_read_b128 v[188:191], v155
	ds_read_b128 v[192:195], v155 offset:1024
	ds_read_b128 v[196:199], v155 offset:2048
	ds_read_b128 v[200:203], v155 offset:3072
	ds_read_b128 v[204:207], v155 offset:4096
	ds_read_b128 v[212:215], v155 offset:5120
	ds_read_b128 v[216:219], v155 offset:6144
	ds_read_b128 v[220:223], v155 offset:7168
	global_load_lds_dwordx4 v[208:209], off
	v_lshl_add_u64 v[208:209], v[148:149], 0, s[40:41]
	s_add_i32 m0, s29, 0xe000
	s_nop 0
	global_load_lds_dwordx4 v[208:209], off
	s_waitcnt vmcnt(8)
	s_waitcnt lgkmcnt(0)
	s_barrier
	s_setprio 0
	s_waitcnt lgkmcnt(0)
	v_mfma_f32_16x16x32_bf16 v[126:129], v[156:159], v[188:191], v[126:129]
	v_mfma_f32_16x16x32_bf16 v[122:125], v[164:167], v[188:191], v[122:125]
	v_mfma_f32_16x16x32_bf16 v[118:121], v[156:159], v[196:199], v[118:121]
	v_mfma_f32_16x16x32_bf16 v[114:117], v[164:167], v[196:199], v[114:117]
	v_mfma_f32_16x16x32_bf16 v[102:105], v[156:159], v[204:207], v[102:105]
	v_mfma_f32_16x16x32_bf16 v[98:101], v[164:167], v[204:207], v[98:101]
	v_mfma_f32_16x16x32_bf16 v[86:89], v[156:159], v[216:219], v[86:89]
	v_mfma_f32_16x16x32_bf16 v[82:85], v[164:167], v[216:219], v[82:85]
	v_mfma_f32_16x16x32_bf16 v[126:129], v[160:163], v[192:195], v[126:129]
	v_mfma_f32_16x16x32_bf16 v[122:125], v[168:171], v[192:195], v[122:125]
	v_mfma_f32_16x16x32_bf16 v[118:121], v[160:163], v[200:203], v[118:121]
	v_mfma_f32_16x16x32_bf16 v[114:117], v[168:171], v[200:203], v[114:117]
	v_mfma_f32_16x16x32_bf16 v[102:105], v[160:163], v[212:215], v[102:105]
	v_mfma_f32_16x16x32_bf16 v[98:101], v[168:171], v[212:215], v[98:101]
	v_mfma_f32_16x16x32_bf16 v[86:89], v[160:163], v[220:223], v[86:89]
	v_mfma_f32_16x16x32_bf16 v[82:85], v[168:171], v[220:223], v[82:85]
	v_mfma_f32_16x16x32_bf16 v[110:113], v[172:175], v[188:191], v[110:113]
	v_mfma_f32_16x16x32_bf16 v[106:109], v[180:183], v[188:191], v[106:109]
	v_mfma_f32_16x16x32_bf16 v[94:97], v[172:175], v[196:199], v[94:97]
	v_mfma_f32_16x16x32_bf16 v[90:93], v[180:183], v[196:199], v[90:93]
	v_mfma_f32_16x16x32_bf16 v[78:81], v[172:175], v[204:207], v[78:81]
	v_mfma_f32_16x16x32_bf16 v[74:77], v[180:183], v[204:207], v[74:77]
	v_mfma_f32_16x16x32_bf16 v[70:73], v[172:175], v[216:219], v[70:73]
	v_mfma_f32_16x16x32_bf16 v[66:69], v[180:183], v[216:219], v[66:69]
	v_mfma_f32_16x16x32_bf16 v[110:113], v[176:179], v[192:195], v[110:113]
	v_mfma_f32_16x16x32_bf16 v[106:109], v[184:187], v[192:195], v[106:109]
	v_mfma_f32_16x16x32_bf16 v[94:97], v[176:179], v[200:203], v[94:97]
	v_mfma_f32_16x16x32_bf16 v[90:93], v[184:187], v[200:203], v[90:93]
	v_mfma_f32_16x16x32_bf16 v[78:81], v[176:179], v[212:215], v[78:81]
	v_mfma_f32_16x16x32_bf16 v[74:77], v[184:187], v[212:215], v[74:77]
	v_mfma_f32_16x16x32_bf16 v[70:73], v[176:179], v[220:223], v[70:73]
	v_mfma_f32_16x16x32_bf16 v[66:69], v[184:187], v[220:223], v[66:69]
	s_setprio 1
	s_barrier
	s_add_i32 s40, s70, s62
	v_lshl_add_u64 v[208:209], s[44:45], 0, v[132:133]
	s_mov_b32 m0, s40
	ds_read_b128 v[188:191], v155 offset:16384
	ds_read_b128 v[192:195], v155 offset:17408
	ds_read_b128 v[196:199], v155 offset:18432
	ds_read_b128 v[200:203], v155 offset:19456
	ds_read_b128 v[204:207], v155 offset:20480
	ds_read_b128 v[212:215], v155 offset:21504
	ds_read_b128 v[216:219], v155 offset:22528
	ds_read_b128 v[220:223], v155 offset:23552
	global_load_lds_dwordx4 v[208:209], off
	s_add_i32 m0, s40, 0x2000
	s_add_u32 s40, s44, 0x20000
	v_lshl_add_u64 v[224:225], s[44:45], 0, v[136:137]
	s_addc_u32 s41, s45, 0
	s_add_i32 s60, s71, s62
	global_load_lds_dwordx4 v[224:225], off
	v_lshl_add_u64 v[226:227], s[40:41], 0, v[132:133]
	s_mov_b32 m0, s60
	v_lshl_add_u64 v[228:229], s[46:47], 0, v[134:135]
	global_load_lds_dwordx4 v[226:227], off
	v_lshl_add_u64 v[226:227], s[40:41], 0, v[136:137]
	s_add_i32 m0, s60, 0x2000
	s_nop 0
	global_load_lds_dwordx4 v[226:227], off
	v_lshl_add_u64 v[226:227], s[46:47], 0, v[130:131]
	s_mov_b32 m0, s29
	s_nop 0
	global_load_lds_dwordx4 v[226:227], off
	s_mov_b32 m0, s63
	s_nop 0
	global_load_lds_dwordx4 v[228:229], off
	s_waitcnt vmcnt(8)
	s_waitcnt lgkmcnt(0)
	s_barrier
	s_setprio 0
	s_waitcnt lgkmcnt(0)
	v_mfma_f32_16x16x32_bf16 v[62:65], v[156:159], v[188:191], v[62:65]
	v_mfma_f32_16x16x32_bf16 v[58:61], v[164:167], v[188:191], v[58:61]
	v_mfma_f32_16x16x32_bf16 v[54:57], v[156:159], v[196:199], v[54:57]
	v_mfma_f32_16x16x32_bf16 v[50:53], v[164:167], v[196:199], v[50:53]
	v_mfma_f32_16x16x32_bf16 v[38:41], v[156:159], v[204:207], v[38:41]
	v_mfma_f32_16x16x32_bf16 v[34:37], v[164:167], v[204:207], v[34:37]
	v_mfma_f32_16x16x32_bf16 v[22:25], v[156:159], v[216:219], v[22:25]
	v_mfma_f32_16x16x32_bf16 v[18:21], v[164:167], v[216:219], v[18:21]
	v_mfma_f32_16x16x32_bf16 v[62:65], v[160:163], v[192:195], v[62:65]
	v_mfma_f32_16x16x32_bf16 v[58:61], v[168:171], v[192:195], v[58:61]
	v_mfma_f32_16x16x32_bf16 v[54:57], v[160:163], v[200:203], v[54:57]
	v_mfma_f32_16x16x32_bf16 v[50:53], v[168:171], v[200:203], v[50:53]
	v_mfma_f32_16x16x32_bf16 v[38:41], v[160:163], v[212:215], v[38:41]
	v_mfma_f32_16x16x32_bf16 v[34:37], v[168:171], v[212:215], v[34:37]
	v_mfma_f32_16x16x32_bf16 v[22:25], v[160:163], v[220:223], v[22:25]
	v_mfma_f32_16x16x32_bf16 v[18:21], v[168:171], v[220:223], v[18:21]
	v_mfma_f32_16x16x32_bf16 v[46:49], v[172:175], v[188:191], v[46:49]
	v_mfma_f32_16x16x32_bf16 v[42:45], v[180:183], v[188:191], v[42:45]
	v_mfma_f32_16x16x32_bf16 v[30:33], v[172:175], v[196:199], v[30:33]
	v_mfma_f32_16x16x32_bf16 v[26:29], v[180:183], v[196:199], v[26:29]
	v_mfma_f32_16x16x32_bf16 v[14:17], v[172:175], v[204:207], v[14:17]
	v_mfma_f32_16x16x32_bf16 v[10:13], v[180:183], v[204:207], v[10:13]
	v_mfma_f32_16x16x32_bf16 v[6:9], v[172:175], v[216:219], v[6:9]
	v_mfma_f32_16x16x32_bf16 v[2:5], v[180:183], v[216:219], v[2:5]
	v_mfma_f32_16x16x32_bf16 v[46:49], v[176:179], v[192:195], v[46:49]
	v_mfma_f32_16x16x32_bf16 v[42:45], v[184:187], v[192:195], v[42:45]
	v_mfma_f32_16x16x32_bf16 v[30:33], v[176:179], v[200:203], v[30:33]
	v_mfma_f32_16x16x32_bf16 v[26:29], v[184:187], v[200:203], v[26:29]
	v_mfma_f32_16x16x32_bf16 v[14:17], v[176:179], v[212:215], v[14:17]
	v_mfma_f32_16x16x32_bf16 v[10:13], v[184:187], v[212:215], v[10:13]
	v_mfma_f32_16x16x32_bf16 v[6:9], v[176:179], v[220:223], v[6:9]
	v_mfma_f32_16x16x32_bf16 v[2:5], v[184:187], v[220:223], v[2:5]
	s_setprio 1
	s_barrier
	s_add_i32 s60, 0, 0x18000
	s_add_i32 s61, 0, 0x1c000
	v_add_u32_e32 v168, s60, v151
	v_add_u32_e32 v184, s61, v151
	ds_read_b128 v[156:159], v168
	ds_read_b128 v[160:163], v168 offset:1024
	ds_read_b128 v[164:167], v168 offset:2048
	ds_read_b128 v[168:171], v168 offset:3072
	ds_read_b128 v[172:175], v184
	ds_read_b128 v[176:179], v184 offset:1024
	ds_read_b128 v[180:183], v184 offset:2048
	ds_read_b128 v[184:187], v184 offset:3072
	s_add_u32 s40, s46, 0x80000
	s_addc_u32 s41, s47, 0
	s_mov_b32 m0, s64
	v_lshl_add_u64 v[230:231], s[40:41], 0, v[130:131]
	ds_read_b128 v[188:191], v155 offset:32768
	ds_read_b128 v[192:195], v155 offset:33792
	ds_read_b128 v[196:199], v155 offset:34816
	ds_read_b128 v[200:203], v155 offset:35840
	ds_read_b128 v[204:207], v155 offset:36864
	ds_read_b128 v[212:215], v155 offset:37888
	ds_read_b128 v[216:219], v155 offset:38912
	ds_read_b128 v[220:223], v155 offset:39936
	global_load_lds_dwordx4 v[230:231], off
	v_lshl_add_u64 v[230:231], s[40:41], 0, v[134:135]
	s_mov_b32 m0, s65
	s_nop 0
	global_load_lds_dwordx4 v[230:231], off
	s_waitcnt vmcnt(8)
	s_waitcnt lgkmcnt(0)
	s_barrier
	s_setprio 0
	s_waitcnt lgkmcnt(0)
	v_mfma_f32_16x16x32_bf16 v[126:129], v[156:159], v[188:191], v[126:129]
	v_mfma_f32_16x16x32_bf16 v[122:125], v[164:167], v[188:191], v[122:125]
	v_mfma_f32_16x16x32_bf16 v[118:121], v[156:159], v[196:199], v[118:121]
	v_mfma_f32_16x16x32_bf16 v[114:117], v[164:167], v[196:199], v[114:117]
	v_mfma_f32_16x16x32_bf16 v[102:105], v[156:159], v[204:207], v[102:105]
	v_mfma_f32_16x16x32_bf16 v[98:101], v[164:167], v[204:207], v[98:101]
	v_mfma_f32_16x16x32_bf16 v[86:89], v[156:159], v[216:219], v[86:89]
	v_mfma_f32_16x16x32_bf16 v[82:85], v[164:167], v[216:219], v[82:85]
	v_mfma_f32_16x16x32_bf16 v[126:129], v[160:163], v[192:195], v[126:129]
	v_mfma_f32_16x16x32_bf16 v[122:125], v[168:171], v[192:195], v[122:125]
	v_mfma_f32_16x16x32_bf16 v[118:121], v[160:163], v[200:203], v[118:121]
	v_mfma_f32_16x16x32_bf16 v[114:117], v[168:171], v[200:203], v[114:117]
	v_mfma_f32_16x16x32_bf16 v[102:105], v[160:163], v[212:215], v[102:105]
	v_mfma_f32_16x16x32_bf16 v[98:101], v[168:171], v[212:215], v[98:101]
	v_mfma_f32_16x16x32_bf16 v[86:89], v[160:163], v[220:223], v[86:89]
	v_mfma_f32_16x16x32_bf16 v[82:85], v[168:171], v[220:223], v[82:85]
	v_mfma_f32_16x16x32_bf16 v[110:113], v[172:175], v[188:191], v[110:113]
	v_mfma_f32_16x16x32_bf16 v[106:109], v[180:183], v[188:191], v[106:109]
	v_mfma_f32_16x16x32_bf16 v[94:97], v[172:175], v[196:199], v[94:97]
	v_mfma_f32_16x16x32_bf16 v[90:93], v[180:183], v[196:199], v[90:93]
	v_mfma_f32_16x16x32_bf16 v[78:81], v[172:175], v[204:207], v[78:81]
	v_mfma_f32_16x16x32_bf16 v[74:77], v[180:183], v[204:207], v[74:77]
	v_mfma_f32_16x16x32_bf16 v[70:73], v[172:175], v[216:219], v[70:73]
	v_mfma_f32_16x16x32_bf16 v[66:69], v[180:183], v[216:219], v[66:69]
	v_mfma_f32_16x16x32_bf16 v[110:113], v[176:179], v[192:195], v[110:113]
	v_mfma_f32_16x16x32_bf16 v[106:109], v[184:187], v[192:195], v[106:109]
	v_mfma_f32_16x16x32_bf16 v[94:97], v[176:179], v[200:203], v[94:97]
	v_mfma_f32_16x16x32_bf16 v[90:93], v[184:187], v[200:203], v[90:93]
	v_mfma_f32_16x16x32_bf16 v[78:81], v[176:179], v[212:215], v[78:81]
	v_mfma_f32_16x16x32_bf16 v[74:77], v[184:187], v[212:215], v[74:77]
	v_mfma_f32_16x16x32_bf16 v[70:73], v[176:179], v[220:223], v[70:73]
	v_mfma_f32_16x16x32_bf16 v[66:69], v[184:187], v[220:223], v[66:69]
	s_setprio 1
	s_barrier
	s_add_i32 s40, s60, s62
	v_lshl_add_u64 v[208:209], v[208:209], 0, s[10:11]
	s_mov_b32 m0, s40
	ds_read_b128 v[188:191], v155 offset:49152
	ds_read_b128 v[192:195], v155 offset:50176
	ds_read_b128 v[196:199], v155 offset:51200
	ds_read_b128 v[200:203], v155 offset:52224
	ds_read_b128 v[204:207], v155 offset:53248
	ds_read_b128 v[212:215], v155 offset:54272
	ds_read_b128 v[216:219], v155 offset:55296
	ds_read_b128 v[220:223], v155 offset:56320
	global_load_lds_dwordx4 v[208:209], off
	s_add_i32 m0, s40, 0x2000
	s_add_u32 s40, s44, 0x20080
	v_lshl_add_u64 v[208:209], v[224:225], 0, s[10:11]
	s_addc_u32 s41, s45, 0
	s_add_i32 s44, s61, s62
	global_load_lds_dwordx4 v[208:209], off
	v_lshl_add_u64 v[208:209], s[40:41], 0, v[132:133]
	s_mov_b32 m0, s44
	s_nop 0
	global_load_lds_dwordx4 v[208:209], off
	v_lshl_add_u64 v[208:209], s[40:41], 0, v[136:137]
	s_add_i32 m0, s44, 0x2000
	s_nop 0
	global_load_lds_dwordx4 v[208:209], off
	v_lshl_add_u64 v[208:209], v[226:227], 0, s[10:11]
	s_mov_b32 m0, s67
	s_nop 0
	global_load_lds_dwordx4 v[208:209], off
	v_lshl_add_u64 v[208:209], v[228:229], 0, s[10:11]
	s_mov_b32 m0, s68
	s_nop 0
	global_load_lds_dwordx4 v[208:209], off
	s_waitcnt vmcnt(8)
	s_waitcnt lgkmcnt(0)
	s_barrier
	s_setprio 0
	s_waitcnt lgkmcnt(0)
	v_mfma_f32_16x16x32_bf16 v[62:65], v[156:159], v[188:191], v[62:65]
	v_mfma_f32_16x16x32_bf16 v[58:61], v[164:167], v[188:191], v[58:61]
	v_mfma_f32_16x16x32_bf16 v[54:57], v[156:159], v[196:199], v[54:57]
	v_mfma_f32_16x16x32_bf16 v[50:53], v[164:167], v[196:199], v[50:53]
	v_mfma_f32_16x16x32_bf16 v[38:41], v[156:159], v[204:207], v[38:41]
	v_mfma_f32_16x16x32_bf16 v[34:37], v[164:167], v[204:207], v[34:37]
	v_mfma_f32_16x16x32_bf16 v[22:25], v[156:159], v[216:219], v[22:25]
	v_mfma_f32_16x16x32_bf16 v[18:21], v[164:167], v[216:219], v[18:21]
	v_mfma_f32_16x16x32_bf16 v[62:65], v[160:163], v[192:195], v[62:65]
	v_mfma_f32_16x16x32_bf16 v[58:61], v[168:171], v[192:195], v[58:61]
	v_mfma_f32_16x16x32_bf16 v[54:57], v[160:163], v[200:203], v[54:57]
	v_mfma_f32_16x16x32_bf16 v[50:53], v[168:171], v[200:203], v[50:53]
	v_mfma_f32_16x16x32_bf16 v[38:41], v[160:163], v[212:215], v[38:41]
	v_mfma_f32_16x16x32_bf16 v[34:37], v[168:171], v[212:215], v[34:37]
	v_mfma_f32_16x16x32_bf16 v[22:25], v[160:163], v[220:223], v[22:25]
	v_mfma_f32_16x16x32_bf16 v[18:21], v[168:171], v[220:223], v[18:21]
	v_mfma_f32_16x16x32_bf16 v[46:49], v[172:175], v[188:191], v[46:49]
	v_mfma_f32_16x16x32_bf16 v[42:45], v[180:183], v[188:191], v[42:45]
	v_mfma_f32_16x16x32_bf16 v[30:33], v[172:175], v[196:199], v[30:33]
	v_mfma_f32_16x16x32_bf16 v[26:29], v[180:183], v[196:199], v[26:29]
	v_mfma_f32_16x16x32_bf16 v[14:17], v[172:175], v[204:207], v[14:17]
	v_mfma_f32_16x16x32_bf16 v[10:13], v[180:183], v[204:207], v[10:13]
	v_mfma_f32_16x16x32_bf16 v[6:9], v[172:175], v[216:219], v[6:9]
	v_mfma_f32_16x16x32_bf16 v[2:5], v[180:183], v[216:219], v[2:5]
	v_mfma_f32_16x16x32_bf16 v[46:49], v[176:179], v[192:195], v[46:49]
	v_mfma_f32_16x16x32_bf16 v[42:45], v[184:187], v[192:195], v[42:45]
	v_mfma_f32_16x16x32_bf16 v[30:33], v[176:179], v[200:203], v[30:33]
	v_mfma_f32_16x16x32_bf16 v[26:29], v[184:187], v[200:203], v[26:29]
	v_mfma_f32_16x16x32_bf16 v[14:17], v[176:179], v[212:215], v[14:17]
	v_mfma_f32_16x16x32_bf16 v[10:13], v[184:187], v[212:215], v[10:13]
	v_mfma_f32_16x16x32_bf16 v[6:9], v[176:179], v[220:223], v[6:9]
	v_mfma_f32_16x16x32_bf16 v[2:5], v[184:187], v[220:223], v[2:5]
	s_setprio 1
	s_barrier
	s_add_i32 s79, s79, 2
	s_cmp_gt_u32 s79, 5
	s_mov_b64 s[40:41], s[42:43]
	s_cbranch_scc0 .LBB0_911
	s_and_b64 vcc, exec, s[12:13]
	s_cbranch_vccz .LBB0_914
	s_barrier

.LBB0_988:
	ds_read_b128 v[66:69], v215
	ds_read_b128 v[70:73], v215 offset:1024
	ds_read_b128 v[74:77], v215 offset:2048
	ds_read_b128 v[78:81], v215 offset:3072
	ds_read_b128 v[82:85], v216
	ds_read_b128 v[86:89], v216 offset:1024
	ds_read_b128 v[90:93], v216 offset:2048
	ds_read_b128 v[94:97], v216 offset:3072
	s_add_u32 s46, s6, 0xfffc0080
	s_addc_u32 s47, s7, -1
	s_cmp_eq_u32 s81, 12
	s_cselect_b32 s49, s39, s47
	s_cselect_b32 s48, s45, s46
	s_cselect_b32 s47, s37, s80
	s_cselect_b32 s46, s78, s79
	v_lshl_add_u64 v[220:221], s[6:7], 0, v[194:195]
	s_add_i32 m0, s64, 0xc000
	ds_read_b128 v[162:165], v217
	ds_read_b128 v[166:169], v217 offset:1024
	ds_read_b128 v[170:173], v217 offset:2048
	ds_read_b128 v[174:177], v217 offset:3072
	ds_read_b128 v[178:181], v217 offset:4096
	ds_read_b128 v[182:185], v217 offset:5120
	ds_read_b128 v[202:205], v217 offset:6144
	ds_read_b128 v[206:209], v217 offset:7168
	global_load_lds_dwordx4 v[220:221], off
	v_lshl_add_u64 v[220:221], s[6:7], 0, v[196:197]
	s_add_i32 m0, s64, 0xe000
	s_nop 0
	global_load_lds_dwordx4 v[220:221], off
	s_waitcnt vmcnt(8)
	s_waitcnt lgkmcnt(0)
	s_barrier
	s_setprio 0
	s_waitcnt lgkmcnt(0)
	v_mfma_f32_16x16x32_bf16 v[158:161], v[66:69], v[162:165], v[158:161]
	v_mfma_f32_16x16x32_bf16 v[154:157], v[74:77], v[162:165], v[154:157]
	v_mfma_f32_16x16x32_bf16 v[142:145], v[66:69], v[170:173], v[142:145]
	v_mfma_f32_16x16x32_bf16 v[138:141], v[74:77], v[170:173], v[138:141]
	v_mfma_f32_16x16x32_bf16 v[126:129], v[66:69], v[178:181], v[126:129]
	v_mfma_f32_16x16x32_bf16 v[122:125], v[74:77], v[178:181], v[122:125]
	v_mfma_f32_16x16x32_bf16 v[110:113], v[66:69], v[202:205], v[110:113]
	v_mfma_f32_16x16x32_bf16 v[106:109], v[74:77], v[202:205], v[106:109]
	v_mfma_f32_16x16x32_bf16 v[158:161], v[70:73], v[166:169], v[158:161]
	v_mfma_f32_16x16x32_bf16 v[154:157], v[78:81], v[166:169], v[154:157]
	v_mfma_f32_16x16x32_bf16 v[142:145], v[70:73], v[174:177], v[142:145]
	v_mfma_f32_16x16x32_bf16 v[138:141], v[78:81], v[174:177], v[138:141]
	v_mfma_f32_16x16x32_bf16 v[126:129], v[70:73], v[182:185], v[126:129]
	v_mfma_f32_16x16x32_bf16 v[122:125], v[78:81], v[182:185], v[122:125]
	v_mfma_f32_16x16x32_bf16 v[110:113], v[70:73], v[206:209], v[110:113]
	v_mfma_f32_16x16x32_bf16 v[106:109], v[78:81], v[206:209], v[106:109]
	v_mfma_f32_16x16x32_bf16 v[150:153], v[82:85], v[162:165], v[150:153]
	v_mfma_f32_16x16x32_bf16 v[146:149], v[90:93], v[162:165], v[146:149]
	v_mfma_f32_16x16x32_bf16 v[134:137], v[82:85], v[170:173], v[134:137]
	v_mfma_f32_16x16x32_bf16 v[130:133], v[90:93], v[170:173], v[130:133]
	v_mfma_f32_16x16x32_bf16 v[118:121], v[82:85], v[178:181], v[118:121]
	v_mfma_f32_16x16x32_bf16 v[114:117], v[90:93], v[178:181], v[114:117]
	v_mfma_f32_16x16x32_bf16 v[102:105], v[82:85], v[202:205], v[102:105]
	v_mfma_f32_16x16x32_bf16 v[98:101], v[90:93], v[202:205], v[98:101]
	v_mfma_f32_16x16x32_bf16 v[150:153], v[86:89], v[166:169], v[150:153]
	v_mfma_f32_16x16x32_bf16 v[146:149], v[94:97], v[166:169], v[146:149]
	v_mfma_f32_16x16x32_bf16 v[134:137], v[86:89], v[174:177], v[134:137]
	v_mfma_f32_16x16x32_bf16 v[130:133], v[94:97], v[174:177], v[130:133]
	v_mfma_f32_16x16x32_bf16 v[118:121], v[86:89], v[182:185], v[118:121]
	v_mfma_f32_16x16x32_bf16 v[114:117], v[94:97], v[182:185], v[114:117]
	v_mfma_f32_16x16x32_bf16 v[102:105], v[86:89], v[206:209], v[102:105]
	v_mfma_f32_16x16x32_bf16 v[98:101], v[94:97], v[206:209], v[98:101]
	s_setprio 1
	s_barrier
	s_add_i32 s60, s75, s63
	v_lshl_add_u64 v[220:221], s[46:47], 0, v[188:189]
	s_mov_b32 m0, s60
	ds_read_b128 v[162:165], v217 offset:16384
	ds_read_b128 v[166:169], v217 offset:17408
	ds_read_b128 v[170:173], v217 offset:18432
	ds_read_b128 v[174:177], v217 offset:19456
	ds_read_b128 v[178:181], v217 offset:20480
	ds_read_b128 v[182:185], v217 offset:21504
	ds_read_b128 v[202:205], v217 offset:22528
	ds_read_b128 v[206:209], v217 offset:23552
	global_load_lds_dwordx4 v[220:221], off
	s_add_i32 m0, s60, 0x2000
	s_add_u32 s60, s46, 0x40000
	v_lshl_add_u64 v[222:223], s[46:47], 0, v[192:193]
	s_addc_u32 s61, s47, 0
	s_add_i32 s82, s76, s63
	global_load_lds_dwordx4 v[222:223], off
	v_lshl_add_u64 v[224:225], s[60:61], 0, v[188:189]
	s_mov_b32 m0, s82
	v_lshl_add_u64 v[226:227], s[48:49], 0, v[190:191]
	global_load_lds_dwordx4 v[224:225], off
	v_lshl_add_u64 v[224:225], s[60:61], 0, v[192:193]
	s_add_i32 m0, s82, 0x2000
	s_nop 0
	global_load_lds_dwordx4 v[224:225], off
	v_lshl_add_u64 v[224:225], s[48:49], 0, v[186:187]
	s_mov_b32 m0, s64
	s_nop 0
	global_load_lds_dwordx4 v[224:225], off
	s_mov_b32 m0, s65
	s_nop 0
	global_load_lds_dwordx4 v[226:227], off
	s_waitcnt vmcnt(8)
	s_waitcnt lgkmcnt(0)
	s_barrier
	s_setprio 0
	s_waitcnt lgkmcnt(0)
	v_mfma_f32_16x16x32_bf16 v[62:65], v[66:69], v[162:165], v[62:65]
	v_mfma_f32_16x16x32_bf16 v[58:61], v[74:77], v[162:165], v[58:61]
	v_mfma_f32_16x16x32_bf16 v[46:49], v[66:69], v[170:173], v[46:49]
	v_mfma_f32_16x16x32_bf16 v[42:45], v[74:77], v[170:173], v[42:45]
	v_mfma_f32_16x16x32_bf16 v[30:33], v[66:69], v[178:181], v[30:33]
	v_mfma_f32_16x16x32_bf16 v[26:29], v[74:77], v[178:181], v[26:29]
	v_mfma_f32_16x16x32_bf16 v[14:17], v[66:69], v[202:205], v[14:17]
	v_mfma_f32_16x16x32_bf16 v[10:13], v[74:77], v[202:205], v[10:13]
	v_mfma_f32_16x16x32_bf16 v[62:65], v[70:73], v[166:169], v[62:65]
	v_mfma_f32_16x16x32_bf16 v[58:61], v[78:81], v[166:169], v[58:61]
	v_mfma_f32_16x16x32_bf16 v[46:49], v[70:73], v[174:177], v[46:49]
	v_mfma_f32_16x16x32_bf16 v[42:45], v[78:81], v[174:177], v[42:45]
	v_mfma_f32_16x16x32_bf16 v[30:33], v[70:73], v[182:185], v[30:33]
	v_mfma_f32_16x16x32_bf16 v[26:29], v[78:81], v[182:185], v[26:29]
	v_mfma_f32_16x16x32_bf16 v[14:17], v[70:73], v[206:209], v[14:17]
	v_mfma_f32_16x16x32_bf16 v[10:13], v[78:81], v[206:209], v[10:13]
	v_mfma_f32_16x16x32_bf16 v[54:57], v[82:85], v[162:165], v[54:57]
	v_mfma_f32_16x16x32_bf16 v[50:53], v[90:93], v[162:165], v[50:53]
	v_mfma_f32_16x16x32_bf16 v[38:41], v[82:85], v[170:173], v[38:41]
	v_mfma_f32_16x16x32_bf16 v[34:37], v[90:93], v[170:173], v[34:37]
	v_mfma_f32_16x16x32_bf16 v[22:25], v[82:85], v[178:181], v[22:25]
	v_mfma_f32_16x16x32_bf16 v[18:21], v[90:93], v[178:181], v[18:21]
	v_mfma_f32_16x16x32_bf16 v[6:9], v[82:85], v[202:205], v[6:9]
	v_mfma_f32_16x16x32_bf16 v[2:5], v[90:93], v[202:205], v[2:5]
	v_mfma_f32_16x16x32_bf16 v[54:57], v[86:89], v[166:169], v[54:57]
	v_mfma_f32_16x16x32_bf16 v[50:53], v[94:97], v[166:169], v[50:53]
	v_mfma_f32_16x16x32_bf16 v[38:41], v[86:89], v[174:177], v[38:41]
	v_mfma_f32_16x16x32_bf16 v[34:37], v[94:97], v[174:177], v[34:37]
	v_mfma_f32_16x16x32_bf16 v[22:25], v[86:89], v[182:185], v[22:25]
	v_mfma_f32_16x16x32_bf16 v[18:21], v[94:97], v[182:185], v[18:21]
	v_mfma_f32_16x16x32_bf16 v[6:9], v[86:89], v[206:209], v[6:9]
	v_mfma_f32_16x16x32_bf16 v[2:5], v[94:97], v[206:209], v[2:5]
	s_setprio 1
	s_barrier
	s_add_i32 s60, 0, 0x18000
	s_add_i32 s61, 0, 0x1c000
	v_add_u32_e32 v78, s60, v213
	v_add_u32_e32 v94, s61, v213
	ds_read_b128 v[66:69], v78
	ds_read_b128 v[70:73], v78 offset:1024
	ds_read_b128 v[74:77], v78 offset:2048
	ds_read_b128 v[78:81], v78 offset:3072
	ds_read_b128 v[82:85], v94
	ds_read_b128 v[86:89], v94 offset:1024
	ds_read_b128 v[90:93], v94 offset:2048
	ds_read_b128 v[94:97], v94 offset:3072
	s_add_u32 s48, s48, 0x40000
	s_addc_u32 s49, s49, 0
	s_mov_b32 m0, s66
	v_lshl_add_u64 v[228:229], s[48:49], 0, v[186:187]
	ds_read_b128 v[162:165], v217 offset:32768
	ds_read_b128 v[166:169], v217 offset:33792
	ds_read_b128 v[170:173], v217 offset:34816
	ds_read_b128 v[174:177], v217 offset:35840
	ds_read_b128 v[178:181], v217 offset:36864
	ds_read_b128 v[182:185], v217 offset:37888
	ds_read_b128 v[202:205], v217 offset:38912
	ds_read_b128 v[206:209], v217 offset:39936
	global_load_lds_dwordx4 v[228:229], off
	v_lshl_add_u64 v[228:229], s[48:49], 0, v[190:191]
	s_mov_b32 m0, s67
	s_nop 0
	global_load_lds_dwordx4 v[228:229], off
	s_waitcnt vmcnt(8)
	s_waitcnt lgkmcnt(0)
	s_barrier
	s_setprio 0
	s_waitcnt lgkmcnt(0)
	v_mfma_f32_16x16x32_bf16 v[158:161], v[66:69], v[162:165], v[158:161]
	v_mfma_f32_16x16x32_bf16 v[154:157], v[74:77], v[162:165], v[154:157]
	v_mfma_f32_16x16x32_bf16 v[142:145], v[66:69], v[170:173], v[142:145]
	v_mfma_f32_16x16x32_bf16 v[138:141], v[74:77], v[170:173], v[138:141]
	v_mfma_f32_16x16x32_bf16 v[126:129], v[66:69], v[178:181], v[126:129]
	v_mfma_f32_16x16x32_bf16 v[122:125], v[74:77], v[178:181], v[122:125]
	v_mfma_f32_16x16x32_bf16 v[110:113], v[66:69], v[202:205], v[110:113]
	v_mfma_f32_16x16x32_bf16 v[106:109], v[74:77], v[202:205], v[106:109]
	v_mfma_f32_16x16x32_bf16 v[158:161], v[70:73], v[166:169], v[158:161]
	v_mfma_f32_16x16x32_bf16 v[154:157], v[78:81], v[166:169], v[154:157]
	v_mfma_f32_16x16x32_bf16 v[142:145], v[70:73], v[174:177], v[142:145]
	v_mfma_f32_16x16x32_bf16 v[138:141], v[78:81], v[174:177], v[138:141]
	v_mfma_f32_16x16x32_bf16 v[126:129], v[70:73], v[182:185], v[126:129]
	v_mfma_f32_16x16x32_bf16 v[122:125], v[78:81], v[182:185], v[122:125]
	v_mfma_f32_16x16x32_bf16 v[110:113], v[70:73], v[206:209], v[110:113]
	v_mfma_f32_16x16x32_bf16 v[106:109], v[78:81], v[206:209], v[106:109]
	v_mfma_f32_16x16x32_bf16 v[150:153], v[82:85], v[162:165], v[150:153]
	v_mfma_f32_16x16x32_bf16 v[146:149], v[90:93], v[162:165], v[146:149]
	v_mfma_f32_16x16x32_bf16 v[134:137], v[82:85], v[170:173], v[134:137]
	v_mfma_f32_16x16x32_bf16 v[130:133], v[90:93], v[170:173], v[130:133]
	v_mfma_f32_16x16x32_bf16 v[118:121], v[82:85], v[178:181], v[118:121]
	v_mfma_f32_16x16x32_bf16 v[114:117], v[90:93], v[178:181], v[114:117]
	v_mfma_f32_16x16x32_bf16 v[102:105], v[82:85], v[202:205], v[102:105]
	v_mfma_f32_16x16x32_bf16 v[98:101], v[90:93], v[202:205], v[98:101]
	v_mfma_f32_16x16x32_bf16 v[150:153], v[86:89], v[166:169], v[150:153]
	v_mfma_f32_16x16x32_bf16 v[146:149], v[94:97], v[166:169], v[146:149]
	v_mfma_f32_16x16x32_bf16 v[134:137], v[86:89], v[174:177], v[134:137]
	v_mfma_f32_16x16x32_bf16 v[130:133], v[94:97], v[174:177], v[130:133]
	v_mfma_f32_16x16x32_bf16 v[118:121], v[86:89], v[182:185], v[118:121]
	v_mfma_f32_16x16x32_bf16 v[114:117], v[94:97], v[182:185], v[114:117]
	v_mfma_f32_16x16x32_bf16 v[102:105], v[86:89], v[206:209], v[102:105]
	v_mfma_f32_16x16x32_bf16 v[98:101], v[94:97], v[206:209], v[98:101]
	s_setprio 1
	s_barrier
	s_add_i32 s48, s60, s63
	v_lshl_add_u64 v[220:221], v[220:221], 0, s[24:25]
	s_mov_b32 m0, s48
	ds_read_b128 v[162:165], v217 offset:49152
	ds_read_b128 v[166:169], v217 offset:50176
	ds_read_b128 v[170:173], v217 offset:51200
	ds_read_b128 v[174:177], v217 offset:52224
	ds_read_b128 v[178:181], v217 offset:53248
	ds_read_b128 v[182:185], v217 offset:54272
	ds_read_b128 v[202:205], v217 offset:55296
	ds_read_b128 v[206:209], v217 offset:56320
	global_load_lds_dwordx4 v[220:221], off
	s_add_i32 m0, s48, 0x2000
	s_add_u32 s46, s46, 0x40080
	v_lshl_add_u64 v[220:221], v[222:223], 0, s[24:25]
	s_addc_u32 s47, s47, 0
	s_add_i32 s48, s61, s63
	global_load_lds_dwordx4 v[220:221], off
	v_lshl_add_u64 v[220:221], s[46:47], 0, v[188:189]
	s_mov_b32 m0, s48
	s_nop 0
	global_load_lds_dwordx4 v[220:221], off
	v_lshl_add_u64 v[220:221], s[46:47], 0, v[192:193]
	s_add_i32 m0, s48, 0x2000
	s_nop 0
	global_load_lds_dwordx4 v[220:221], off
	v_lshl_add_u64 v[220:221], v[224:225], 0, s[24:25]
	s_mov_b32 m0, s72
	s_nop 0
	global_load_lds_dwordx4 v[220:221], off
	v_lshl_add_u64 v[220:221], v[226:227], 0, s[24:25]
	s_mov_b32 m0, s73
	s_nop 0
	global_load_lds_dwordx4 v[220:221], off
	s_waitcnt vmcnt(8)
	s_waitcnt lgkmcnt(0)
	s_barrier
	s_setprio 0
	s_waitcnt lgkmcnt(0)
	v_mfma_f32_16x16x32_bf16 v[62:65], v[66:69], v[162:165], v[62:65]
	v_mfma_f32_16x16x32_bf16 v[58:61], v[74:77], v[162:165], v[58:61]
	v_mfma_f32_16x16x32_bf16 v[46:49], v[66:69], v[170:173], v[46:49]
	v_mfma_f32_16x16x32_bf16 v[42:45], v[74:77], v[170:173], v[42:45]
	v_mfma_f32_16x16x32_bf16 v[30:33], v[66:69], v[178:181], v[30:33]
	v_mfma_f32_16x16x32_bf16 v[26:29], v[74:77], v[178:181], v[26:29]
	v_mfma_f32_16x16x32_bf16 v[14:17], v[66:69], v[202:205], v[14:17]
	v_mfma_f32_16x16x32_bf16 v[10:13], v[74:77], v[202:205], v[10:13]
	v_mfma_f32_16x16x32_bf16 v[62:65], v[70:73], v[166:169], v[62:65]
	v_mfma_f32_16x16x32_bf16 v[58:61], v[78:81], v[166:169], v[58:61]
	v_mfma_f32_16x16x32_bf16 v[46:49], v[70:73], v[174:177], v[46:49]
	v_mfma_f32_16x16x32_bf16 v[42:45], v[78:81], v[174:177], v[42:45]
	v_mfma_f32_16x16x32_bf16 v[30:33], v[70:73], v[182:185], v[30:33]
	v_mfma_f32_16x16x32_bf16 v[26:29], v[78:81], v[182:185], v[26:29]
	v_mfma_f32_16x16x32_bf16 v[14:17], v[70:73], v[206:209], v[14:17]
	v_mfma_f32_16x16x32_bf16 v[10:13], v[78:81], v[206:209], v[10:13]
	v_mfma_f32_16x16x32_bf16 v[54:57], v[82:85], v[162:165], v[54:57]
	v_mfma_f32_16x16x32_bf16 v[50:53], v[90:93], v[162:165], v[50:53]
	v_mfma_f32_16x16x32_bf16 v[38:41], v[82:85], v[170:173], v[38:41]
	v_mfma_f32_16x16x32_bf16 v[34:37], v[90:93], v[170:173], v[34:37]
	v_mfma_f32_16x16x32_bf16 v[22:25], v[82:85], v[178:181], v[22:25]
	v_mfma_f32_16x16x32_bf16 v[18:21], v[90:93], v[178:181], v[18:21]
	v_mfma_f32_16x16x32_bf16 v[6:9], v[82:85], v[202:205], v[6:9]
	v_mfma_f32_16x16x32_bf16 v[2:5], v[90:93], v[202:205], v[2:5]
	v_mfma_f32_16x16x32_bf16 v[54:57], v[86:89], v[166:169], v[54:57]
	v_mfma_f32_16x16x32_bf16 v[50:53], v[94:97], v[166:169], v[50:53]
	v_mfma_f32_16x16x32_bf16 v[38:41], v[86:89], v[174:177], v[38:41]
	v_mfma_f32_16x16x32_bf16 v[34:37], v[94:97], v[174:177], v[34:37]
	v_mfma_f32_16x16x32_bf16 v[22:25], v[86:89], v[182:185], v[22:25]
	v_mfma_f32_16x16x32_bf16 v[18:21], v[94:97], v[182:185], v[18:21]
	v_mfma_f32_16x16x32_bf16 v[6:9], v[86:89], v[206:209], v[6:9]
	v_mfma_f32_16x16x32_bf16 v[2:5], v[94:97], v[206:209], v[2:5]
	s_setprio 1
	s_barrier
	s_add_i32 s81, s81, 2
	s_add_u32 s6, s6, 0x100
	s_addc_u32 s7, s7, 0
	s_add_u32 s79, s79, 0x100
	s_addc_u32 s80, s80, 0
	s_cmp_gt_u32 s81, 13
	s_cbranch_scc0 .LBB0_988
	s_and_b64 vcc, exec, s[28:29]
	s_cbranch_vccz .LBB0_991
	s_barrier

.LBB0_1087:
	ds_read_b128 v[130:133], v165
	ds_read_b128 v[134:137], v165 offset:1024
	ds_read_b128 v[138:141], v165 offset:2048
	ds_read_b128 v[142:145], v165 offset:3072
	ds_read_b128 v[168:171], v166
	ds_read_b128 v[172:175], v166 offset:1024
	ds_read_b128 v[176:179], v166 offset:2048
	ds_read_b128 v[180:183], v166 offset:3072
	s_add_u32 s28, s26, 0xfffc0080
	s_addc_u32 s29, s27, -1
	s_cmp_eq_u32 s69, 12
	s_cselect_b32 s31, s17, s29
	s_cselect_b32 s30, s65, s28
	s_cselect_b32 s29, s15, s68
	s_cselect_b32 s28, s66, s67
	v_lshl_add_u64 v[216:217], s[26:27], 0, v[154:155]
	s_add_i32 m0, s25, 0xc000
	ds_read_b128 v[184:187], v167
	ds_read_b128 v[188:191], v167 offset:1024
	ds_read_b128 v[192:195], v167 offset:2048
	ds_read_b128 v[196:199], v167 offset:3072
	ds_read_b128 v[200:203], v167 offset:4096
	ds_read_b128 v[204:207], v167 offset:5120
	ds_read_b128 v[208:211], v167 offset:6144
	ds_read_b128 v[212:215], v167 offset:7168
	global_load_lds_dwordx4 v[216:217], off
	v_lshl_add_u64 v[216:217], s[26:27], 0, v[156:157]
	s_add_i32 m0, s25, 0xe000
	s_nop 0
	global_load_lds_dwordx4 v[216:217], off
	s_waitcnt vmcnt(8)
	s_waitcnt lgkmcnt(0)
	s_barrier
	s_setprio 0
	s_waitcnt lgkmcnt(0)
	v_mfma_f32_16x16x32_bf16 v[126:129], v[130:133], v[184:187], v[126:129]
	v_mfma_f32_16x16x32_bf16 v[122:125], v[138:141], v[184:187], v[122:125]
	v_mfma_f32_16x16x32_bf16 v[110:113], v[130:133], v[192:195], v[110:113]
	v_mfma_f32_16x16x32_bf16 v[106:109], v[138:141], v[192:195], v[106:109]
	v_mfma_f32_16x16x32_bf16 v[94:97], v[130:133], v[200:203], v[94:97]
	v_mfma_f32_16x16x32_bf16 v[90:93], v[138:141], v[200:203], v[90:93]
	v_mfma_f32_16x16x32_bf16 v[78:81], v[130:133], v[208:211], v[78:81]
	v_mfma_f32_16x16x32_bf16 v[74:77], v[138:141], v[208:211], v[74:77]
	v_mfma_f32_16x16x32_bf16 v[126:129], v[134:137], v[188:191], v[126:129]
	v_mfma_f32_16x16x32_bf16 v[122:125], v[142:145], v[188:191], v[122:125]
	v_mfma_f32_16x16x32_bf16 v[110:113], v[134:137], v[196:199], v[110:113]
	v_mfma_f32_16x16x32_bf16 v[106:109], v[142:145], v[196:199], v[106:109]
	v_mfma_f32_16x16x32_bf16 v[94:97], v[134:137], v[204:207], v[94:97]
	v_mfma_f32_16x16x32_bf16 v[90:93], v[142:145], v[204:207], v[90:93]
	v_mfma_f32_16x16x32_bf16 v[78:81], v[134:137], v[212:215], v[78:81]
	v_mfma_f32_16x16x32_bf16 v[74:77], v[142:145], v[212:215], v[74:77]
	v_mfma_f32_16x16x32_bf16 v[118:121], v[168:171], v[184:187], v[118:121]
	v_mfma_f32_16x16x32_bf16 v[114:117], v[176:179], v[184:187], v[114:117]
	v_mfma_f32_16x16x32_bf16 v[102:105], v[168:171], v[192:195], v[102:105]
	v_mfma_f32_16x16x32_bf16 v[98:101], v[176:179], v[192:195], v[98:101]
	v_mfma_f32_16x16x32_bf16 v[86:89], v[168:171], v[200:203], v[86:89]
	v_mfma_f32_16x16x32_bf16 v[82:85], v[176:179], v[200:203], v[82:85]
	v_mfma_f32_16x16x32_bf16 v[70:73], v[168:171], v[208:211], v[70:73]
	v_mfma_f32_16x16x32_bf16 v[66:69], v[176:179], v[208:211], v[66:69]
	v_mfma_f32_16x16x32_bf16 v[118:121], v[172:175], v[188:191], v[118:121]
	v_mfma_f32_16x16x32_bf16 v[114:117], v[180:183], v[188:191], v[114:117]
	v_mfma_f32_16x16x32_bf16 v[102:105], v[172:175], v[196:199], v[102:105]
	v_mfma_f32_16x16x32_bf16 v[98:101], v[180:183], v[196:199], v[98:101]
	v_mfma_f32_16x16x32_bf16 v[86:89], v[172:175], v[204:207], v[86:89]
	v_mfma_f32_16x16x32_bf16 v[82:85], v[180:183], v[204:207], v[82:85]
	v_mfma_f32_16x16x32_bf16 v[70:73], v[172:175], v[212:215], v[70:73]
	v_mfma_f32_16x16x32_bf16 v[66:69], v[180:183], v[212:215], v[66:69]
	s_setprio 1
	s_barrier
	s_add_i32 s60, s49, s37
	v_lshl_add_u64 v[216:217], s[28:29], 0, v[150:151]
	s_mov_b32 m0, s60
	ds_read_b128 v[184:187], v167 offset:16384
	ds_read_b128 v[188:191], v167 offset:17408
	ds_read_b128 v[192:195], v167 offset:18432
	ds_read_b128 v[196:199], v167 offset:19456
	ds_read_b128 v[200:203], v167 offset:20480
	ds_read_b128 v[204:207], v167 offset:21504
	ds_read_b128 v[208:211], v167 offset:22528
	ds_read_b128 v[212:215], v167 offset:23552
	global_load_lds_dwordx4 v[216:217], off
	s_add_i32 m0, s60, 0x2000
	s_add_u32 s60, s28, 0x40000
	v_lshl_add_u64 v[218:219], s[28:29], 0, v[146:147]
	s_addc_u32 s61, s29, 0
	s_add_i32 s70, s50, s37
	global_load_lds_dwordx4 v[218:219], off
	v_lshl_add_u64 v[220:221], s[60:61], 0, v[150:151]
	s_mov_b32 m0, s70
	v_lshl_add_u64 v[222:223], s[30:31], 0, v[148:149]
	global_load_lds_dwordx4 v[220:221], off
	v_lshl_add_u64 v[220:221], s[60:61], 0, v[146:147]
	s_add_i32 m0, s70, 0x2000
	s_nop 0
	global_load_lds_dwordx4 v[220:221], off
	v_lshl_add_u64 v[220:221], s[30:31], 0, v[152:153]
	s_mov_b32 m0, s25
	s_nop 0
	global_load_lds_dwordx4 v[220:221], off
	s_mov_b32 m0, s43
	s_nop 0
	global_load_lds_dwordx4 v[222:223], off
	s_waitcnt vmcnt(8)
	s_waitcnt lgkmcnt(0)
	s_barrier
	s_setprio 0
	s_waitcnt lgkmcnt(0)
	v_mfma_f32_16x16x32_bf16 v[62:65], v[130:133], v[184:187], v[62:65]
	v_mfma_f32_16x16x32_bf16 v[58:61], v[138:141], v[184:187], v[58:61]
	v_mfma_f32_16x16x32_bf16 v[46:49], v[130:133], v[192:195], v[46:49]
	v_mfma_f32_16x16x32_bf16 v[42:45], v[138:141], v[192:195], v[42:45]
	v_mfma_f32_16x16x32_bf16 v[30:33], v[130:133], v[200:203], v[30:33]
	v_mfma_f32_16x16x32_bf16 v[26:29], v[138:141], v[200:203], v[26:29]
	v_mfma_f32_16x16x32_bf16 v[14:17], v[130:133], v[208:211], v[14:17]
	v_mfma_f32_16x16x32_bf16 v[10:13], v[138:141], v[208:211], v[10:13]
	v_mfma_f32_16x16x32_bf16 v[62:65], v[134:137], v[188:191], v[62:65]
	v_mfma_f32_16x16x32_bf16 v[58:61], v[142:145], v[188:191], v[58:61]
	v_mfma_f32_16x16x32_bf16 v[46:49], v[134:137], v[196:199], v[46:49]
	v_mfma_f32_16x16x32_bf16 v[42:45], v[142:145], v[196:199], v[42:45]
	v_mfma_f32_16x16x32_bf16 v[30:33], v[134:137], v[204:207], v[30:33]
	v_mfma_f32_16x16x32_bf16 v[26:29], v[142:145], v[204:207], v[26:29]
	v_mfma_f32_16x16x32_bf16 v[14:17], v[134:137], v[212:215], v[14:17]
	v_mfma_f32_16x16x32_bf16 v[10:13], v[142:145], v[212:215], v[10:13]
	v_mfma_f32_16x16x32_bf16 v[54:57], v[168:171], v[184:187], v[54:57]
	v_mfma_f32_16x16x32_bf16 v[50:53], v[176:179], v[184:187], v[50:53]
	v_mfma_f32_16x16x32_bf16 v[38:41], v[168:171], v[192:195], v[38:41]
	v_mfma_f32_16x16x32_bf16 v[34:37], v[176:179], v[192:195], v[34:37]
	v_mfma_f32_16x16x32_bf16 v[22:25], v[168:171], v[200:203], v[22:25]
	v_mfma_f32_16x16x32_bf16 v[18:21], v[176:179], v[200:203], v[18:21]
	v_mfma_f32_16x16x32_bf16 v[6:9], v[168:171], v[208:211], v[6:9]
	v_mfma_f32_16x16x32_bf16 v[2:5], v[176:179], v[208:211], v[2:5]
	v_mfma_f32_16x16x32_bf16 v[54:57], v[172:175], v[188:191], v[54:57]
	v_mfma_f32_16x16x32_bf16 v[50:53], v[180:183], v[188:191], v[50:53]
	v_mfma_f32_16x16x32_bf16 v[38:41], v[172:175], v[196:199], v[38:41]
	v_mfma_f32_16x16x32_bf16 v[34:37], v[180:183], v[196:199], v[34:37]
	v_mfma_f32_16x16x32_bf16 v[22:25], v[172:175], v[204:207], v[22:25]
	v_mfma_f32_16x16x32_bf16 v[18:21], v[180:183], v[204:207], v[18:21]
	v_mfma_f32_16x16x32_bf16 v[6:9], v[172:175], v[212:215], v[6:9]
	v_mfma_f32_16x16x32_bf16 v[2:5], v[180:183], v[212:215], v[2:5]
	s_setprio 1
	s_barrier
	s_add_i32 s60, 0, 0x18000
	s_add_i32 s61, 0, 0x1c000
	v_add_u32_e32 v142, s60, v163
	v_add_u32_e32 v180, s61, v163
	ds_read_b128 v[130:133], v142
	ds_read_b128 v[134:137], v142 offset:1024
	ds_read_b128 v[138:141], v142 offset:2048
	ds_read_b128 v[142:145], v142 offset:3072
	ds_read_b128 v[168:171], v180
	ds_read_b128 v[172:175], v180 offset:1024
	ds_read_b128 v[176:179], v180 offset:2048
	ds_read_b128 v[180:183], v180 offset:3072
	s_add_u32 s30, s30, 0x40000
	s_addc_u32 s31, s31, 0
	s_mov_b32 m0, s44
	v_lshl_add_u64 v[224:225], s[30:31], 0, v[152:153]
	ds_read_b128 v[184:187], v167 offset:32768
	ds_read_b128 v[188:191], v167 offset:33792
	ds_read_b128 v[192:195], v167 offset:34816
	ds_read_b128 v[196:199], v167 offset:35840
	ds_read_b128 v[200:203], v167 offset:36864
	ds_read_b128 v[204:207], v167 offset:37888
	ds_read_b128 v[208:211], v167 offset:38912
	ds_read_b128 v[212:215], v167 offset:39936
	global_load_lds_dwordx4 v[224:225], off
	v_lshl_add_u64 v[224:225], s[30:31], 0, v[148:149]
	s_mov_b32 m0, s45
	s_nop 0
	global_load_lds_dwordx4 v[224:225], off
	s_waitcnt vmcnt(8)
	s_waitcnt lgkmcnt(0)
	s_barrier
	s_setprio 0
	s_waitcnt lgkmcnt(0)
	v_mfma_f32_16x16x32_bf16 v[126:129], v[130:133], v[184:187], v[126:129]
	v_mfma_f32_16x16x32_bf16 v[122:125], v[138:141], v[184:187], v[122:125]
	v_mfma_f32_16x16x32_bf16 v[110:113], v[130:133], v[192:195], v[110:113]
	v_mfma_f32_16x16x32_bf16 v[106:109], v[138:141], v[192:195], v[106:109]
	v_mfma_f32_16x16x32_bf16 v[94:97], v[130:133], v[200:203], v[94:97]
	v_mfma_f32_16x16x32_bf16 v[90:93], v[138:141], v[200:203], v[90:93]
	v_mfma_f32_16x16x32_bf16 v[78:81], v[130:133], v[208:211], v[78:81]
	v_mfma_f32_16x16x32_bf16 v[74:77], v[138:141], v[208:211], v[74:77]
	v_mfma_f32_16x16x32_bf16 v[126:129], v[134:137], v[188:191], v[126:129]
	v_mfma_f32_16x16x32_bf16 v[122:125], v[142:145], v[188:191], v[122:125]
	v_mfma_f32_16x16x32_bf16 v[110:113], v[134:137], v[196:199], v[110:113]
	v_mfma_f32_16x16x32_bf16 v[106:109], v[142:145], v[196:199], v[106:109]
	v_mfma_f32_16x16x32_bf16 v[94:97], v[134:137], v[204:207], v[94:97]
	v_mfma_f32_16x16x32_bf16 v[90:93], v[142:145], v[204:207], v[90:93]
	v_mfma_f32_16x16x32_bf16 v[78:81], v[134:137], v[212:215], v[78:81]
	v_mfma_f32_16x16x32_bf16 v[74:77], v[142:145], v[212:215], v[74:77]
	v_mfma_f32_16x16x32_bf16 v[118:121], v[168:171], v[184:187], v[118:121]
	v_mfma_f32_16x16x32_bf16 v[114:117], v[176:179], v[184:187], v[114:117]
	v_mfma_f32_16x16x32_bf16 v[102:105], v[168:171], v[192:195], v[102:105]
	v_mfma_f32_16x16x32_bf16 v[98:101], v[176:179], v[192:195], v[98:101]
	v_mfma_f32_16x16x32_bf16 v[86:89], v[168:171], v[200:203], v[86:89]
	v_mfma_f32_16x16x32_bf16 v[82:85], v[176:179], v[200:203], v[82:85]
	v_mfma_f32_16x16x32_bf16 v[70:73], v[168:171], v[208:211], v[70:73]
	v_mfma_f32_16x16x32_bf16 v[66:69], v[176:179], v[208:211], v[66:69]
	v_mfma_f32_16x16x32_bf16 v[118:121], v[172:175], v[188:191], v[118:121]
	v_mfma_f32_16x16x32_bf16 v[114:117], v[180:183], v[188:191], v[114:117]
	v_mfma_f32_16x16x32_bf16 v[102:105], v[172:175], v[196:199], v[102:105]
	v_mfma_f32_16x16x32_bf16 v[98:101], v[180:183], v[196:199], v[98:101]
	v_mfma_f32_16x16x32_bf16 v[86:89], v[172:175], v[204:207], v[86:89]
	v_mfma_f32_16x16x32_bf16 v[82:85], v[180:183], v[204:207], v[82:85]
	v_mfma_f32_16x16x32_bf16 v[70:73], v[172:175], v[212:215], v[70:73]
	v_mfma_f32_16x16x32_bf16 v[66:69], v[180:183], v[212:215], v[66:69]
	s_setprio 1
	s_barrier
	s_add_i32 s30, s60, s37
	v_lshl_add_u64 v[216:217], v[216:217], 0, s[10:11]
	s_mov_b32 m0, s30
	ds_read_b128 v[184:187], v167 offset:49152
	ds_read_b128 v[188:191], v167 offset:50176
	ds_read_b128 v[192:195], v167 offset:51200
	ds_read_b128 v[196:199], v167 offset:52224
	ds_read_b128 v[200:203], v167 offset:53248
	ds_read_b128 v[204:207], v167 offset:54272
	ds_read_b128 v[208:211], v167 offset:55296
	ds_read_b128 v[212:215], v167 offset:56320
	global_load_lds_dwordx4 v[216:217], off
	s_add_i32 m0, s30, 0x2000
	s_add_u32 s28, s28, 0x40080
	v_lshl_add_u64 v[216:217], v[218:219], 0, s[10:11]
	s_addc_u32 s29, s29, 0
	s_add_i32 s30, s61, s37
	global_load_lds_dwordx4 v[216:217], off
	v_lshl_add_u64 v[216:217], s[28:29], 0, v[150:151]
	s_mov_b32 m0, s30
	s_nop 0
	global_load_lds_dwordx4 v[216:217], off
	v_lshl_add_u64 v[216:217], s[28:29], 0, v[146:147]
	s_add_i32 m0, s30, 0x2000
	s_nop 0
	global_load_lds_dwordx4 v[216:217], off
	v_lshl_add_u64 v[216:217], v[220:221], 0, s[10:11]
	s_mov_b32 m0, s47
	s_nop 0
	global_load_lds_dwordx4 v[216:217], off
	v_lshl_add_u64 v[216:217], v[222:223], 0, s[10:11]
	s_mov_b32 m0, s48
	s_nop 0
	global_load_lds_dwordx4 v[216:217], off
	s_waitcnt vmcnt(8)
	s_waitcnt lgkmcnt(0)
	s_barrier
	s_setprio 0
	s_waitcnt lgkmcnt(0)
	v_mfma_f32_16x16x32_bf16 v[62:65], v[130:133], v[184:187], v[62:65]
	v_mfma_f32_16x16x32_bf16 v[58:61], v[138:141], v[184:187], v[58:61]
	v_mfma_f32_16x16x32_bf16 v[46:49], v[130:133], v[192:195], v[46:49]
	v_mfma_f32_16x16x32_bf16 v[42:45], v[138:141], v[192:195], v[42:45]
	v_mfma_f32_16x16x32_bf16 v[30:33], v[130:133], v[200:203], v[30:33]
	v_mfma_f32_16x16x32_bf16 v[26:29], v[138:141], v[200:203], v[26:29]
	v_mfma_f32_16x16x32_bf16 v[14:17], v[130:133], v[208:211], v[14:17]
	v_mfma_f32_16x16x32_bf16 v[10:13], v[138:141], v[208:211], v[10:13]
	v_mfma_f32_16x16x32_bf16 v[62:65], v[134:137], v[188:191], v[62:65]
	v_mfma_f32_16x16x32_bf16 v[58:61], v[142:145], v[188:191], v[58:61]
	v_mfma_f32_16x16x32_bf16 v[46:49], v[134:137], v[196:199], v[46:49]
	v_mfma_f32_16x16x32_bf16 v[42:45], v[142:145], v[196:199], v[42:45]
	v_mfma_f32_16x16x32_bf16 v[30:33], v[134:137], v[204:207], v[30:33]
	v_mfma_f32_16x16x32_bf16 v[26:29], v[142:145], v[204:207], v[26:29]
	v_mfma_f32_16x16x32_bf16 v[14:17], v[134:137], v[212:215], v[14:17]
	v_mfma_f32_16x16x32_bf16 v[10:13], v[142:145], v[212:215], v[10:13]
	v_mfma_f32_16x16x32_bf16 v[54:57], v[168:171], v[184:187], v[54:57]
	v_mfma_f32_16x16x32_bf16 v[50:53], v[176:179], v[184:187], v[50:53]
	v_mfma_f32_16x16x32_bf16 v[38:41], v[168:171], v[192:195], v[38:41]
	v_mfma_f32_16x16x32_bf16 v[34:37], v[176:179], v[192:195], v[34:37]
	v_mfma_f32_16x16x32_bf16 v[22:25], v[168:171], v[200:203], v[22:25]
	v_mfma_f32_16x16x32_bf16 v[18:21], v[176:179], v[200:203], v[18:21]
	v_mfma_f32_16x16x32_bf16 v[6:9], v[168:171], v[208:211], v[6:9]
	v_mfma_f32_16x16x32_bf16 v[2:5], v[176:179], v[208:211], v[2:5]
	v_mfma_f32_16x16x32_bf16 v[54:57], v[172:175], v[188:191], v[54:57]
	v_mfma_f32_16x16x32_bf16 v[50:53], v[180:183], v[188:191], v[50:53]
	v_mfma_f32_16x16x32_bf16 v[38:41], v[172:175], v[196:199], v[38:41]
	v_mfma_f32_16x16x32_bf16 v[34:37], v[180:183], v[196:199], v[34:37]
	v_mfma_f32_16x16x32_bf16 v[22:25], v[172:175], v[204:207], v[22:25]
	v_mfma_f32_16x16x32_bf16 v[18:21], v[180:183], v[204:207], v[18:21]
	v_mfma_f32_16x16x32_bf16 v[6:9], v[172:175], v[212:215], v[6:9]
	v_mfma_f32_16x16x32_bf16 v[2:5], v[180:183], v[212:215], v[2:5]
	s_setprio 1
	s_barrier
	s_add_i32 s69, s69, 2
	s_add_u32 s26, s26, 0x100
	s_addc_u32 s27, s27, 0
	s_add_u32 s67, s67, 0x100
	s_addc_u32 s68, s68, 0
	s_cmp_gt_u32 s69, 13
	s_cbranch_scc0 .LBB0_1087
	s_and_b64 vcc, exec, s[12:13]
	s_cbranch_vccz .LBB0_1090
	s_barrier

.LBB0_1168:
	ds_read_b128 v[104:107], v201
	ds_read_b128 v[108:111], v201 offset:1024
	ds_read_b128 v[116:119], v201 offset:2048
	ds_read_b128 v[124:127], v201 offset:3072
	ds_read_b128 v[162:165], v202
	ds_read_b128 v[166:169], v202 offset:1024
	ds_read_b128 v[170:173], v202 offset:2048
	ds_read_b128 v[174:177], v202 offset:3072
	s_add_u32 s28, s26, 0xfff50080
	s_addc_u32 s29, s27, -1
	s_cmp_eq_u32 s59, 40
	s_cselect_b32 s31, s11, s29
	s_cselect_b32 s30, s10, s28
	s_cselect_b32 s29, s19, s25
	s_cselect_b32 s28, s18, s23
	v_lshl_add_u64 v[244:245], s[26:27], 0, v[154:155]
	s_add_i32 m0, s38, 0xc000
	ds_read_b128 v[178:181], v203
	ds_read_b128 v[216:219], v203 offset:1024
	ds_read_b128 v[220:223], v203 offset:2048
	ds_read_b128 v[224:227], v203 offset:3072
	ds_read_b128 v[228:231], v203 offset:4096
	ds_read_b128 v[232:235], v203 offset:5120
	ds_read_b128 v[236:239], v203 offset:6144
	ds_read_b128 v[240:243], v203 offset:7168
	global_load_lds_dwordx4 v[244:245], off
	v_lshl_add_u64 v[244:245], s[26:27], 0, v[156:157]
	s_add_i32 m0, s38, 0xe000
	s_nop 0
	global_load_lds_dwordx4 v[244:245], off
	s_waitcnt vmcnt(8)
	s_waitcnt lgkmcnt(0)
	s_barrier
	s_setprio 0
	s_waitcnt lgkmcnt(0)
	v_mfma_f32_16x16x32_bf16 v[140:143], v[104:107], v[178:181], v[140:143]
	v_mfma_f32_16x16x32_bf16 v[136:139], v[116:119], v[178:181], v[136:139]
	v_mfma_f32_16x16x32_bf16 v[120:123], v[104:107], v[220:223], v[120:123]
	v_mfma_f32_16x16x32_bf16 v[112:115], v[116:119], v[220:223], v[112:115]
	v_mfma_f32_16x16x32_bf16 v[92:95], v[104:107], v[228:231], v[92:95]
	v_mfma_f32_16x16x32_bf16 v[88:91], v[116:119], v[228:231], v[88:91]
	v_mfma_f32_16x16x32_bf16 v[76:79], v[104:107], v[236:239], v[76:79]
	v_mfma_f32_16x16x32_bf16 v[72:75], v[116:119], v[236:239], v[72:75]
	v_mfma_f32_16x16x32_bf16 v[140:143], v[108:111], v[216:219], v[140:143]
	v_mfma_f32_16x16x32_bf16 v[136:139], v[124:127], v[216:219], v[136:139]
	v_mfma_f32_16x16x32_bf16 v[120:123], v[108:111], v[224:227], v[120:123]
	v_mfma_f32_16x16x32_bf16 v[112:115], v[124:127], v[224:227], v[112:115]
	v_mfma_f32_16x16x32_bf16 v[92:95], v[108:111], v[232:235], v[92:95]
	v_mfma_f32_16x16x32_bf16 v[88:91], v[124:127], v[232:235], v[88:91]
	v_mfma_f32_16x16x32_bf16 v[76:79], v[108:111], v[240:243], v[76:79]
	v_mfma_f32_16x16x32_bf16 v[72:75], v[124:127], v[240:243], v[72:75]
	v_mfma_f32_16x16x32_bf16 v[132:135], v[162:165], v[178:181], v[132:135]
	v_mfma_f32_16x16x32_bf16 v[128:131], v[170:173], v[178:181], v[128:131]
	v_mfma_f32_16x16x32_bf16 v[100:103], v[162:165], v[220:223], v[100:103]
	v_mfma_f32_16x16x32_bf16 v[96:99], v[170:173], v[220:223], v[96:99]
	v_mfma_f32_16x16x32_bf16 v[84:87], v[162:165], v[228:231], v[84:87]
	v_mfma_f32_16x16x32_bf16 v[80:83], v[170:173], v[228:231], v[80:83]
	v_mfma_f32_16x16x32_bf16 v[68:71], v[162:165], v[236:239], v[68:71]
	v_mfma_f32_16x16x32_bf16 v[64:67], v[170:173], v[236:239], v[64:67]
	v_mfma_f32_16x16x32_bf16 v[132:135], v[166:169], v[216:219], v[132:135]
	v_mfma_f32_16x16x32_bf16 v[128:131], v[174:177], v[216:219], v[128:131]
	v_mfma_f32_16x16x32_bf16 v[100:103], v[166:169], v[224:227], v[100:103]
	v_mfma_f32_16x16x32_bf16 v[96:99], v[174:177], v[224:227], v[96:99]
	v_mfma_f32_16x16x32_bf16 v[84:87], v[166:169], v[232:235], v[84:87]
	v_mfma_f32_16x16x32_bf16 v[80:83], v[174:177], v[232:235], v[80:83]
	v_mfma_f32_16x16x32_bf16 v[68:71], v[166:169], v[240:243], v[68:71]
	v_mfma_f32_16x16x32_bf16 v[64:67], v[174:177], v[240:243], v[64:67]
	s_setprio 1
	s_barrier
	s_add_i32 s60, s51, s37
	v_lshl_add_u64 v[244:245], s[28:29], 0, v[146:147]
	s_mov_b32 m0, s60
	ds_read_b128 v[178:181], v203 offset:16384
	ds_read_b128 v[216:219], v203 offset:17408
	ds_read_b128 v[220:223], v203 offset:18432
	ds_read_b128 v[224:227], v203 offset:19456
	ds_read_b128 v[228:231], v203 offset:20480
	ds_read_b128 v[232:235], v203 offset:21504
	ds_read_b128 v[236:239], v203 offset:22528
	ds_read_b128 v[240:243], v203 offset:23552
	global_load_lds_dwordx4 v[244:245], off
	s_add_i32 m0, s60, 0x2000
	s_add_u32 s60, s28, 0xb0000
	v_lshl_add_u64 v[246:247], s[28:29], 0, v[150:151]
	s_addc_u32 s61, s29, 0
	s_add_i32 s62, s56, s37
	global_load_lds_dwordx4 v[246:247], off
	v_lshl_add_u64 v[248:249], s[60:61], 0, v[146:147]
	s_mov_b32 m0, s62
	v_lshl_add_u64 v[250:251], s[30:31], 0, v[148:149]
	global_load_lds_dwordx4 v[248:249], off
	v_lshl_add_u64 v[248:249], s[60:61], 0, v[150:151]
	s_add_i32 m0, s62, 0x2000
	s_nop 0
	global_load_lds_dwordx4 v[248:249], off
	v_lshl_add_u64 v[248:249], s[30:31], 0, v[144:145]
	s_mov_b32 m0, s38
	s_nop 0
	global_load_lds_dwordx4 v[248:249], off
	s_mov_b32 m0, s39
	s_nop 0
	global_load_lds_dwordx4 v[250:251], off
	s_waitcnt vmcnt(8)
	s_waitcnt lgkmcnt(0)
	s_barrier
	s_setprio 0
	s_waitcnt lgkmcnt(0)
	v_mfma_f32_16x16x32_bf16 v[60:63], v[104:107], v[178:181], v[60:63]
	v_mfma_f32_16x16x32_bf16 v[56:59], v[116:119], v[178:181], v[56:59]
	v_mfma_f32_16x16x32_bf16 v[44:47], v[104:107], v[220:223], v[44:47]
	v_mfma_f32_16x16x32_bf16 v[40:43], v[116:119], v[220:223], v[40:43]
	v_mfma_f32_16x16x32_bf16 v[28:31], v[104:107], v[228:231], v[28:31]
	v_mfma_f32_16x16x32_bf16 v[24:27], v[116:119], v[228:231], v[24:27]
	v_mfma_f32_16x16x32_bf16 v[12:15], v[104:107], v[236:239], v[12:15]
	v_mfma_f32_16x16x32_bf16 v[8:11], v[116:119], v[236:239], v[8:11]
	v_mfma_f32_16x16x32_bf16 v[60:63], v[108:111], v[216:219], v[60:63]
	v_mfma_f32_16x16x32_bf16 v[56:59], v[124:127], v[216:219], v[56:59]
	v_mfma_f32_16x16x32_bf16 v[44:47], v[108:111], v[224:227], v[44:47]
	v_mfma_f32_16x16x32_bf16 v[40:43], v[124:127], v[224:227], v[40:43]
	v_mfma_f32_16x16x32_bf16 v[28:31], v[108:111], v[232:235], v[28:31]
	v_mfma_f32_16x16x32_bf16 v[24:27], v[124:127], v[232:235], v[24:27]
	v_mfma_f32_16x16x32_bf16 v[12:15], v[108:111], v[240:243], v[12:15]
	v_mfma_f32_16x16x32_bf16 v[8:11], v[124:127], v[240:243], v[8:11]
	v_mfma_f32_16x16x32_bf16 v[52:55], v[162:165], v[178:181], v[52:55]
	v_mfma_f32_16x16x32_bf16 v[48:51], v[170:173], v[178:181], v[48:51]
	v_mfma_f32_16x16x32_bf16 v[36:39], v[162:165], v[220:223], v[36:39]
	v_mfma_f32_16x16x32_bf16 v[32:35], v[170:173], v[220:223], v[32:35]
	v_mfma_f32_16x16x32_bf16 v[20:23], v[162:165], v[228:231], v[20:23]
	v_mfma_f32_16x16x32_bf16 v[16:19], v[170:173], v[228:231], v[16:19]
	v_mfma_f32_16x16x32_bf16 v[4:7], v[162:165], v[236:239], v[4:7]
	v_mfma_f32_16x16x32_bf16 v[0:3], v[170:173], v[236:239], v[0:3]
	v_mfma_f32_16x16x32_bf16 v[52:55], v[166:169], v[216:219], v[52:55]
	v_mfma_f32_16x16x32_bf16 v[48:51], v[174:177], v[216:219], v[48:51]
	v_mfma_f32_16x16x32_bf16 v[36:39], v[166:169], v[224:227], v[36:39]
	v_mfma_f32_16x16x32_bf16 v[32:35], v[174:177], v[224:227], v[32:35]
	v_mfma_f32_16x16x32_bf16 v[20:23], v[166:169], v[232:235], v[20:23]
	v_mfma_f32_16x16x32_bf16 v[16:19], v[174:177], v[232:235], v[16:19]
	v_mfma_f32_16x16x32_bf16 v[4:7], v[166:169], v[240:243], v[4:7]
	v_mfma_f32_16x16x32_bf16 v[0:3], v[174:177], v[240:243], v[0:3]
	s_setprio 1
	s_barrier
	s_add_i32 s60, 0, 0x18000
	s_add_i32 s61, 0, 0x1c000
	v_add_u32_e32 v124, s60, v183
	v_add_u32_e32 v174, s61, v183
	ds_read_b128 v[104:107], v124
	ds_read_b128 v[108:111], v124 offset:1024
	ds_read_b128 v[116:119], v124 offset:2048
	ds_read_b128 v[124:127], v124 offset:3072
	ds_read_b128 v[162:165], v174
	ds_read_b128 v[166:169], v174 offset:1024
	ds_read_b128 v[170:173], v174 offset:2048
	ds_read_b128 v[174:177], v174 offset:3072
	s_add_u32 s30, s30, 0xb0000
	s_addc_u32 s31, s31, 0
	s_mov_b32 m0, s40
	v_lshl_add_u64 v[252:253], s[30:31], 0, v[144:145]
	ds_read_b128 v[178:181], v203 offset:32768
	ds_read_b128 v[216:219], v203 offset:33792
	ds_read_b128 v[220:223], v203 offset:34816
	ds_read_b128 v[224:227], v203 offset:35840
	ds_read_b128 v[228:231], v203 offset:36864
	ds_read_b128 v[232:235], v203 offset:37888
	ds_read_b128 v[236:239], v203 offset:38912
	ds_read_b128 v[240:243], v203 offset:39936
	global_load_lds_dwordx4 v[252:253], off
	v_lshl_add_u64 v[252:253], s[30:31], 0, v[148:149]
	s_mov_b32 m0, s41
	s_nop 0
	global_load_lds_dwordx4 v[252:253], off
	s_waitcnt vmcnt(8)
	s_waitcnt lgkmcnt(0)
	s_barrier
	s_setprio 0
	s_waitcnt lgkmcnt(0)
	v_mfma_f32_16x16x32_bf16 v[140:143], v[104:107], v[178:181], v[140:143]
	v_mfma_f32_16x16x32_bf16 v[136:139], v[116:119], v[178:181], v[136:139]
	v_mfma_f32_16x16x32_bf16 v[120:123], v[104:107], v[220:223], v[120:123]
	v_mfma_f32_16x16x32_bf16 v[112:115], v[116:119], v[220:223], v[112:115]
	v_mfma_f32_16x16x32_bf16 v[92:95], v[104:107], v[228:231], v[92:95]
	v_mfma_f32_16x16x32_bf16 v[88:91], v[116:119], v[228:231], v[88:91]
	v_mfma_f32_16x16x32_bf16 v[76:79], v[104:107], v[236:239], v[76:79]
	v_mfma_f32_16x16x32_bf16 v[72:75], v[116:119], v[236:239], v[72:75]
	v_mfma_f32_16x16x32_bf16 v[140:143], v[108:111], v[216:219], v[140:143]
	v_mfma_f32_16x16x32_bf16 v[136:139], v[124:127], v[216:219], v[136:139]
	v_mfma_f32_16x16x32_bf16 v[120:123], v[108:111], v[224:227], v[120:123]
	v_mfma_f32_16x16x32_bf16 v[112:115], v[124:127], v[224:227], v[112:115]
	v_mfma_f32_16x16x32_bf16 v[92:95], v[108:111], v[232:235], v[92:95]
	v_mfma_f32_16x16x32_bf16 v[88:91], v[124:127], v[232:235], v[88:91]
	v_mfma_f32_16x16x32_bf16 v[76:79], v[108:111], v[240:243], v[76:79]
	v_mfma_f32_16x16x32_bf16 v[72:75], v[124:127], v[240:243], v[72:75]
	v_mfma_f32_16x16x32_bf16 v[132:135], v[162:165], v[178:181], v[132:135]
	v_mfma_f32_16x16x32_bf16 v[128:131], v[170:173], v[178:181], v[128:131]
	v_mfma_f32_16x16x32_bf16 v[100:103], v[162:165], v[220:223], v[100:103]
	v_mfma_f32_16x16x32_bf16 v[96:99], v[170:173], v[220:223], v[96:99]
	v_mfma_f32_16x16x32_bf16 v[84:87], v[162:165], v[228:231], v[84:87]
	v_mfma_f32_16x16x32_bf16 v[80:83], v[170:173], v[228:231], v[80:83]
	v_mfma_f32_16x16x32_bf16 v[68:71], v[162:165], v[236:239], v[68:71]
	v_mfma_f32_16x16x32_bf16 v[64:67], v[170:173], v[236:239], v[64:67]
	v_mfma_f32_16x16x32_bf16 v[132:135], v[166:169], v[216:219], v[132:135]
	v_mfma_f32_16x16x32_bf16 v[128:131], v[174:177], v[216:219], v[128:131]
	v_mfma_f32_16x16x32_bf16 v[100:103], v[166:169], v[224:227], v[100:103]
	v_mfma_f32_16x16x32_bf16 v[96:99], v[174:177], v[224:227], v[96:99]
	v_mfma_f32_16x16x32_bf16 v[84:87], v[166:169], v[232:235], v[84:87]
	v_mfma_f32_16x16x32_bf16 v[80:83], v[174:177], v[232:235], v[80:83]
	v_mfma_f32_16x16x32_bf16 v[68:71], v[166:169], v[240:243], v[68:71]
	v_mfma_f32_16x16x32_bf16 v[64:67], v[174:177], v[240:243], v[64:67]
	s_setprio 1
	s_barrier
	s_add_i32 s30, s60, s37
	v_lshl_add_u64 v[244:245], v[244:245], 0, s[14:15]
	s_mov_b32 m0, s30
	ds_read_b128 v[178:181], v203 offset:49152
	ds_read_b128 v[216:219], v203 offset:50176
	ds_read_b128 v[220:223], v203 offset:51200
	ds_read_b128 v[224:227], v203 offset:52224
	ds_read_b128 v[228:231], v203 offset:53248
	ds_read_b128 v[232:235], v203 offset:54272
	ds_read_b128 v[236:239], v203 offset:55296
	ds_read_b128 v[240:243], v203 offset:56320
	global_load_lds_dwordx4 v[244:245], off
	s_add_i32 m0, s30, 0x2000
	s_add_u32 s28, s28, 0xb0080
	v_lshl_add_u64 v[244:245], v[246:247], 0, s[14:15]
	s_addc_u32 s29, s29, 0
	s_add_i32 s30, s61, s37
	global_load_lds_dwordx4 v[244:245], off
	v_lshl_add_u64 v[244:245], s[28:29], 0, v[146:147]
	s_mov_b32 m0, s30
	s_nop 0
	global_load_lds_dwordx4 v[244:245], off
	v_lshl_add_u64 v[244:245], s[28:29], 0, v[150:151]
	s_add_i32 m0, s30, 0x2000
	s_nop 0
	global_load_lds_dwordx4 v[244:245], off
	v_lshl_add_u64 v[244:245], v[248:249], 0, s[14:15]
	s_mov_b32 m0, s48
	s_nop 0
	global_load_lds_dwordx4 v[244:245], off
	v_lshl_add_u64 v[244:245], v[250:251], 0, s[14:15]
	s_mov_b32 m0, s49
	s_nop 0
	global_load_lds_dwordx4 v[244:245], off
	s_waitcnt vmcnt(8)
	s_waitcnt lgkmcnt(0)
	s_barrier
	s_setprio 0
	s_waitcnt lgkmcnt(0)
	v_mfma_f32_16x16x32_bf16 v[60:63], v[104:107], v[178:181], v[60:63]
	v_mfma_f32_16x16x32_bf16 v[56:59], v[116:119], v[178:181], v[56:59]
	v_mfma_f32_16x16x32_bf16 v[44:47], v[104:107], v[220:223], v[44:47]
	v_mfma_f32_16x16x32_bf16 v[40:43], v[116:119], v[220:223], v[40:43]
	v_mfma_f32_16x16x32_bf16 v[28:31], v[104:107], v[228:231], v[28:31]
	v_mfma_f32_16x16x32_bf16 v[24:27], v[116:119], v[228:231], v[24:27]
	v_mfma_f32_16x16x32_bf16 v[12:15], v[104:107], v[236:239], v[12:15]
	v_mfma_f32_16x16x32_bf16 v[8:11], v[116:119], v[236:239], v[8:11]
	v_mfma_f32_16x16x32_bf16 v[60:63], v[108:111], v[216:219], v[60:63]
	v_mfma_f32_16x16x32_bf16 v[56:59], v[124:127], v[216:219], v[56:59]
	v_mfma_f32_16x16x32_bf16 v[44:47], v[108:111], v[224:227], v[44:47]
	v_mfma_f32_16x16x32_bf16 v[40:43], v[124:127], v[224:227], v[40:43]
	v_mfma_f32_16x16x32_bf16 v[28:31], v[108:111], v[232:235], v[28:31]
	v_mfma_f32_16x16x32_bf16 v[24:27], v[124:127], v[232:235], v[24:27]
	v_mfma_f32_16x16x32_bf16 v[12:15], v[108:111], v[240:243], v[12:15]
	v_mfma_f32_16x16x32_bf16 v[8:11], v[124:127], v[240:243], v[8:11]
	v_mfma_f32_16x16x32_bf16 v[52:55], v[162:165], v[178:181], v[52:55]
	v_mfma_f32_16x16x32_bf16 v[48:51], v[170:173], v[178:181], v[48:51]
	v_mfma_f32_16x16x32_bf16 v[36:39], v[162:165], v[220:223], v[36:39]
	v_mfma_f32_16x16x32_bf16 v[32:35], v[170:173], v[220:223], v[32:35]
	v_mfma_f32_16x16x32_bf16 v[20:23], v[162:165], v[228:231], v[20:23]
	v_mfma_f32_16x16x32_bf16 v[16:19], v[170:173], v[228:231], v[16:19]
	v_mfma_f32_16x16x32_bf16 v[4:7], v[162:165], v[236:239], v[4:7]
	v_mfma_f32_16x16x32_bf16 v[0:3], v[170:173], v[236:239], v[0:3]
	v_mfma_f32_16x16x32_bf16 v[52:55], v[166:169], v[216:219], v[52:55]
	v_mfma_f32_16x16x32_bf16 v[48:51], v[174:177], v[216:219], v[48:51]
	v_mfma_f32_16x16x32_bf16 v[36:39], v[166:169], v[224:227], v[36:39]
	v_mfma_f32_16x16x32_bf16 v[32:35], v[174:177], v[224:227], v[32:35]
	v_mfma_f32_16x16x32_bf16 v[20:23], v[166:169], v[232:235], v[20:23]
	v_mfma_f32_16x16x32_bf16 v[16:19], v[174:177], v[232:235], v[16:19]
	v_mfma_f32_16x16x32_bf16 v[4:7], v[166:169], v[240:243], v[4:7]
	v_mfma_f32_16x16x32_bf16 v[0:3], v[174:177], v[240:243], v[0:3]
	s_setprio 1
	s_barrier
	s_add_i32 s59, s59, 2
	s_add_u32 s26, s26, 0x100
	s_addc_u32 s27, s27, 0
	s_add_u32 s23, s23, 0x100
	s_addc_u32 s25, s25, 0
	s_cmp_gt_u32 s59, 41
	s_cbranch_scc0 .LBB0_1168
	s_and_b64 vcc, exec, s[16:17]
	s_cbranch_vccz .LBB0_1171
	s_barrier
